# residual GEMM epilogues: xor-16/xor-32 lane reductions via v_permlane16/32_swap instead of ds_bpermute; FFN-out: dropped acc+0 adds (null bias)
# baseline (speedup 1.0000x reference)
; __device__ __forceinline__ unsigned cvt_pk_bf16(float lo, float hi) { unsigned r; asm volatile("v_cvt_pk_bf16_f32 %0, %1, %2" : "=v"(r) : "v"(lo), "v"(hi)); return r; }
; __device__ __forceinline__ float bflo(unsigned w) { return __uint_as_float(w << 16); }
; __device__ __forceinline__ float bfhi(unsigned w) { return __uint_as_float(w & 0xffff0000u); }
;     __device__ __forceinline__ void operator()(const f32x4 (&acc)[2][2][4][2], const Unit& u, int wr, int wc, int fr, int fq) const {
;         const int row0 = u.pm * BM + wr * 64 + fr, col0 = u.pn * BM + wc * 32 + 8 * fq;
;         f32x4 bv[2][2];
; #pragma unroll
;         for (int bj = 0; bj < 2; ++bj)
; #pragma unroll
;             for (int n = 0; n < 2; ++n) bv[bj][n] = bias ? *(const f32x4*)(bias + col0 + bj * HALF + 4 * n) : (f32x4){0.f, 0.f, 0.f, 0.f};
;         u32x4 cur[2], nxt[2];
;         { const size_t off = (size_t)row0 * 1024 + col0;
; #pragma unroll
;           for (int bj = 0; bj < 2; ++bj) cur[bj] = *(const u32x4*)(xb + off + bj * HALF); }
; #pragma unroll
;         for (int g = 0; g < 8; ++g) { const int ai = g >> 2, m = g & 3; const int row = row0 + ai * HALF + m * 16; const size_t off = (size_t)row * 1024 + col0; float ss = 0.f;
;             if (g < 7) { const int g1 = g + 1; const size_t offn = (size_t)(row0 + (g1 >> 2) * HALF + (g1 & 3) * 16) * 1024 + col0;
; #pragma unroll
;                 for (int bj = 0; bj < 2; ++bj) nxt[bj] = *(const u32x4*)(xb + offn + bj * HALF); }
; #pragma unroll
;             for (int bj = 0; bj < 2; ++bj) { const u32x4 c = cur[bj];
;                 const f32x4 b0 = (f32x4){bflo(c[0]), bfhi(c[0]), bflo(c[1]), bfhi(c[1])}, b1 = (f32x4){bflo(c[2]), bfhi(c[2]), bflo(c[3]), bfhi(c[3])};
;                 const f32x4 v0 = b0 + (acc[ai][bj][m][0] + bv[bj][0]) * scale, v1 = b1 + (acc[ai][bj][m][1] + bv[bj][1]) * scale;
;                 ss += (v0[0] * v0[0] + v0[1] * v0[1]) + (v0[2] * v0[2] + v0[3] * v0[3]) + (v1[0] * v1[0] + v1[1] * v1[1]) + (v1[2] * v1[2] + v1[3] * v1[3]);
;                 u32x4 w; w.x = cvt_pk_bf16(v0[0], v0[1]); w.y = cvt_pk_bf16(v0[2], v0[3]); w.z = cvt_pk_bf16(v1[0], v1[1]); w.w = cvt_pk_bf16(v1[2], v1[3]);
;                 *(u32x4*)(xb + off + bj * HALF) = w; }
;             ss += __shfl_xor(ss, 16); ss += __shfl_xor(ss, 32);
;             if (fq == 0) partn[(size_t)row * 16 + u.pn * 4 + wc] = ss;
.LBB0_277:
	v_lshl_add_u32 v148, s22, 8, v156
	v_lshl_or_b32 v146, s3, 8, v158
	v_ashrrev_i32_e32 v149, 31, v148
	v_ashrrev_i32_e32 v147, 31, v146
	v_lshlrev_b64 v[128:129], 11, v[148:149]
	v_lshl_add_u64 v[128:129], s[18:19], 0, v[128:129]
	v_lshlrev_b64 v[130:131], 1, v[146:147]
	v_lshl_add_u64 v[154:155], v[128:129], 0, v[130:131]
	global_load_dwordx4 v[160:163], v[154:155], off
	global_load_dwordx4 v[164:167], v[154:155], off offset:256
	v_or_b32_e32 v150, 16, v148
	v_ashrrev_i32_e32 v151, 31, v150
	v_lshlrev_b64 v[128:129], 11, v[150:151]
	v_lshl_add_u64 v[128:129], s[18:19], 0, v[128:129]
	v_lshl_add_u64 v[152:153], v[128:129], 0, v[130:131]
	global_load_dwordx4 v[132:135], v[152:153], off
	global_load_dwordx4 v[128:131], v[152:153], off offset:256
	v_add_u32_e32 v250, 0x20, v148
	v_ashrrev_i32_e32 v251, 31, v250
	v_lshlrev_b64 v[250:251], 11, v[250:251]
	v_lshl_add_u64 v[250:251], s[18:19], 0, v[250:251]
	v_lshl_add_u64 v[250:251], v[146:147], 1, v[250:251]
	global_load_dwordx4 v[172:175], v[250:251], off
	global_load_dwordx4 v[176:179], v[250:251], off offset:256
	v_add_u32_e32 v250, 0x30, v148
	v_ashrrev_i32_e32 v251, 31, v250
	v_lshlrev_b64 v[250:251], 11, v[250:251]
	v_lshl_add_u64 v[250:251], s[18:19], 0, v[250:251]
	v_lshl_add_u64 v[250:251], v[146:147], 1, v[250:251]
	global_load_dwordx4 v[186:189], v[250:251], off
	global_load_dwordx4 v[190:193], v[250:251], off offset:256
	v_add_u32_e32 v250, 0x80, v148
	v_ashrrev_i32_e32 v251, 31, v250
	v_lshlrev_b64 v[250:251], 11, v[250:251]
	v_lshl_add_u64 v[250:251], s[18:19], 0, v[250:251]
	v_lshl_add_u64 v[250:251], v[146:147], 1, v[250:251]
	global_load_dwordx4 v[194:197], v[250:251], off
	global_load_dwordx4 v[198:201], v[250:251], off offset:256
	v_add_u32_e32 v250, 0x90, v148
	v_ashrrev_i32_e32 v251, 31, v250
	v_lshlrev_b64 v[250:251], 11, v[250:251]
	v_lshl_add_u64 v[250:251], s[18:19], 0, v[250:251]
	v_lshl_add_u64 v[250:251], v[146:147], 1, v[250:251]
	global_load_dwordx4 v[216:219], v[250:251], off
	global_load_dwordx4 v[224:227], v[250:251], off offset:256
	v_add_u32_e32 v250, 0xa0, v148
	v_ashrrev_i32_e32 v251, 31, v250
	v_lshlrev_b64 v[250:251], 11, v[250:251]
	v_lshl_add_u64 v[250:251], s[18:19], 0, v[250:251]
	v_lshl_add_u64 v[250:251], v[146:147], 1, v[250:251]
	global_load_dwordx4 v[230:233], v[250:251], off
	global_load_dwordx4 v[238:241], v[250:251], off offset:256
	v_add_u32_e32 v250, 0xb0, v148
	v_ashrrev_i32_e32 v251, 31, v250
	v_lshlrev_b64 v[250:251], 11, v[250:251]
	v_lshl_add_u64 v[250:251], s[18:19], 0, v[250:251]
	v_lshl_add_u64 v[250:251], v[146:147], 1, v[250:251]
	global_load_dwordx4 v[242:245], v[250:251], off
	global_load_dwordx4 v[246:249], v[250:251], off offset:256
	s_lshl_b32 s50, s3, 2
	s_ashr_i32 s51, s50, 31
	s_waitcnt vmcnt(14)
	v_lshlrev_b32_e32 v168, 16, v160
	v_and_b32_e32 v169, 0xffff0000, v160
	v_lshlrev_b32_e32 v160, 16, v161
	v_and_b32_e32 v161, 0xffff0000, v161
	v_lshlrev_b32_e32 v170, 16, v162
	v_and_b32_e32 v171, 0xffff0000, v162
	v_lshlrev_b32_e32 v162, 16, v163
	v_and_b32_e32 v163, 0xffff0000, v163
	v_pk_fma_f32 v[126:127], v[126:127], 0.5, v[160:161] op_sel_hi:[1,0,1]
	v_pk_fma_f32 v[124:125], v[124:125], 0.5, v[168:169] op_sel_hi:[1,0,1]
	v_pk_fma_f32 v[160:161], v[122:123], 0.5, v[162:163] op_sel_hi:[1,0,1]
	v_pk_fma_f32 v[122:123], v[120:121], 0.5, v[170:171] op_sel_hi:[1,0,1]
	v_mul_f32_e32 v120, v125, v125
	v_mul_f32_e32 v121, v127, v127
	v_fmac_f32_e32 v120, v124, v124
	v_fmac_f32_e32 v121, v126, v126
	v_add_f32_e32 v120, v120, v121
	v_mul_f32_e32 v121, v123, v123
	v_fmac_f32_e32 v121, v122, v122
	v_add_f32_e32 v120, v121, v120
	v_mul_f32_e32 v121, v161, v161
	v_fmac_f32_e32 v121, v160, v160
	v_add_f32_e32 v162, v121, v120
	v_cvt_pk_bf16_f32 v120, v124, v125
	v_cvt_pk_bf16_f32 v121, v126, v127
	v_cvt_pk_bf16_f32 v122, v122, v123
	v_cvt_pk_bf16_f32 v123, v160, v161
	global_store_dwordx4 v[154:155], v[120:123], off
	v_lshlrev_b32_e32 v124, 16, v166
	v_and_b32_e32 v125, 0xffff0000, v166
	v_lshlrev_b32_e32 v120, 16, v164
	v_and_b32_e32 v121, 0xffff0000, v164
	v_lshlrev_b32_e32 v122, 16, v165
	v_and_b32_e32 v123, 0xffff0000, v165
	v_lshlrev_b32_e32 v126, 16, v167
	v_and_b32_e32 v127, 0xffff0000, v167
	v_pk_fma_f32 v[118:119], v[118:119], 0.5, v[122:123] op_sel_hi:[1,0,1]
	v_pk_fma_f32 v[116:117], v[116:117], 0.5, v[120:121] op_sel_hi:[1,0,1]
	v_pk_fma_f32 v[120:121], v[114:115], 0.5, v[126:127] op_sel_hi:[1,0,1]
	v_pk_fma_f32 v[114:115], v[112:113], 0.5, v[124:125] op_sel_hi:[1,0,1]
	v_mul_f32_e32 v112, v117, v117
	v_mul_f32_e32 v113, v119, v119
	v_fmac_f32_e32 v112, v116, v116
	v_fmac_f32_e32 v113, v118, v118
	v_add_f32_e32 v112, v112, v113
	v_mul_f32_e32 v113, v115, v115
	v_fmac_f32_e32 v113, v114, v114
	v_add_f32_e32 v112, v113, v112
	v_mul_f32_e32 v113, v121, v121
	v_fmac_f32_e32 v113, v120, v120
	v_add_f32_e32 v112, v113, v112
	v_add_f32_e32 v122, v162, v112
	v_cvt_pk_bf16_f32 v112, v116, v117
	v_cvt_pk_bf16_f32 v113, v118, v119
	v_cvt_pk_bf16_f32 v114, v114, v115
	v_cvt_pk_bf16_f32 v115, v120, v121
	global_store_dwordx4 v[154:155], v[112:115], off offset:256
	s_nop 1
	v_and_b32_e32 v113, 64, v212
	v_xor_b32_e32 v112, 16, v212
	v_add_u32_e32 v113, 64, v113
	v_cmp_lt_i32_e32 vcc, v112, v113
	v_xor_b32_e32 v114, 32, v212
	s_nop 0
	v_cndmask_b32_e32 v112, v212, v112, vcc
	v_lshlrev_b32_e32 v124, 2, v112
	v_mov_b32_e32 v112, v122
	s_nop 1
	v_permlane16_swap_b32_e32 v122, v112
	v_cmp_lt_i32_e32 vcc, v114, v113
	s_waitcnt lgkmcnt(0)
	v_add_f32_e32 v112, v122, v112
	v_cndmask_b32_e32 v113, v212, v114, vcc
	v_lshlrev_b32_e32 v125, 2, v113
	v_mov_b32_e32 v113, v112
	s_nop 1
	v_permlane32_swap_b32_e32 v112, v113
	s_and_saveexec_b64 s[22:23], s[6:7]
	s_cbranch_execz .LBB0_279
	v_lshlrev_b64 v[114:115], 6, v[148:149]
	v_lshl_add_u64 v[114:115], s[40:41], 0, v[114:115]
	v_lshl_add_u64 v[114:115], s[50:51], 2, v[114:115]
	s_lshl_b32 s68, s57, 2
	v_lshl_add_u64 v[114:115], v[114:115], 0, s[68:69]
	s_waitcnt lgkmcnt(0)
	v_add_f32_e32 v112, v112, v113
	global_store_dword v[114:115], v112, off
; __device__ __forceinline__ unsigned cvt_pk_bf16(float lo, float hi) { unsigned r; asm volatile("v_cvt_pk_bf16_f32 %0, %1, %2" : "=v"(r) : "v"(lo), "v"(hi)); return r; }
; __device__ __forceinline__ float bflo(unsigned w) { return __uint_as_float(w << 16); }
; __device__ __forceinline__ float bfhi(unsigned w) { return __uint_as_float(w & 0xffff0000u); }
;     __device__ __forceinline__ void operator()(const f32x4 (&acc)[2][2][4][2], const Unit& u, int wr, int wc, int fr, int fq) const {
;     ...
; #pragma unroll
;         for (int g = 0; g < 8; ++g) { const int ai = g >> 2, m = g & 3; const int row = row0 + ai * HALF + m * 16; const size_t off = (size_t)row * 1024 + col0; float ss = 0.f;
;             if (g < 7) { const int g1 = g + 1; const size_t offn = (size_t)(row0 + (g1 >> 2) * HALF + (g1 & 3) * 16) * 1024 + col0;
; #pragma unroll
;                 for (int bj = 0; bj < 2; ++bj) nxt[bj] = *(const u32x4*)(xb + offn + bj * HALF); }
; #pragma unroll
;             for (int bj = 0; bj < 2; ++bj) { const u32x4 c = cur[bj];
;                 const f32x4 b0 = (f32x4){bflo(c[0]), bfhi(c[0]), bflo(c[1]), bfhi(c[1])}, b1 = (f32x4){bflo(c[2]), bfhi(c[2]), bflo(c[3]), bfhi(c[3])};
;                 const f32x4 v0 = b0 + (acc[ai][bj][m][0] + bv[bj][0]) * scale, v1 = b1 + (acc[ai][bj][m][1] + bv[bj][1]) * scale;
;                 ss += (v0[0] * v0[0] + v0[1] * v0[1]) + (v0[2] * v0[2] + v0[3] * v0[3]) + (v1[0] * v1[0] + v1[1] * v1[1]) + (v1[2] * v1[2] + v1[3] * v1[3]);
;                 u32x4 w; w.x = cvt_pk_bf16(v0[0], v0[1]); w.y = cvt_pk_bf16(v0[2], v0[3]); w.z = cvt_pk_bf16(v1[0], v1[1]); w.w = cvt_pk_bf16(v1[2], v1[3]);
;                 *(u32x4*)(xb + off + bj * HALF) = w; }
;             ss += __shfl_xor(ss, 16); ss += __shfl_xor(ss, 32);
;             if (fq == 0) partn[(size_t)row * 16 + u.pn * 4 + wc] = ss;
.LBB0_279:
	s_or_b64 exec, exec, s[22:23]
	v_or_b32_e32 v120, 32, v148
	v_ashrrev_i32_e32 v121, 31, v120
	s_waitcnt lgkmcnt(0)
	v_lshlrev_b64 v[112:113], 11, v[120:121]
	v_lshl_add_u64 v[112:113], s[18:19], 0, v[112:113]
	v_lshl_add_u64 v[122:123], v[146:147], 1, v[112:113]
	s_waitcnt vmcnt(14)
	v_lshlrev_b32_e32 v126, 16, v132
	v_and_b32_e32 v127, 0xffff0000, v132
	v_lshlrev_b32_e32 v132, 16, v133
	v_and_b32_e32 v133, 0xffff0000, v133
	v_lshlrev_b32_e32 v154, 16, v134
	v_and_b32_e32 v155, 0xffff0000, v134
	v_lshlrev_b32_e32 v134, 16, v135
	v_and_b32_e32 v135, 0xffff0000, v135
	v_pk_fma_f32 v[110:111], v[110:111], 0.5, v[132:133] op_sel_hi:[1,0,1]
	v_pk_fma_f32 v[108:109], v[108:109], 0.5, v[126:127] op_sel_hi:[1,0,1]
	v_pk_fma_f32 v[126:127], v[106:107], 0.5, v[134:135] op_sel_hi:[1,0,1]
	v_pk_fma_f32 v[106:107], v[104:105], 0.5, v[154:155] op_sel_hi:[1,0,1]
	v_mul_f32_e32 v104, v109, v109
	v_mul_f32_e32 v105, v111, v111
	v_fmac_f32_e32 v104, v108, v108
	v_fmac_f32_e32 v105, v110, v110
	v_add_f32_e32 v104, v104, v105
	v_mul_f32_e32 v105, v107, v107
	v_fmac_f32_e32 v105, v106, v106
	v_add_f32_e32 v104, v105, v104
	v_mul_f32_e32 v105, v127, v127
	v_fmac_f32_e32 v105, v126, v126
	v_add_f32_e32 v132, v105, v104
	v_cvt_pk_bf16_f32 v104, v108, v109
	v_cvt_pk_bf16_f32 v105, v110, v111
	v_lshlrev_b32_e32 v108, 16, v128
	v_and_b32_e32 v109, 0xffff0000, v128
	v_lshlrev_b32_e32 v110, 16, v129
	v_and_b32_e32 v111, 0xffff0000, v129
	v_lshlrev_b32_e32 v128, 16, v130
	v_and_b32_e32 v129, 0xffff0000, v130
	v_pk_fma_f32 v[102:103], v[102:103], 0.5, v[110:111] op_sel_hi:[1,0,1]
	v_pk_fma_f32 v[100:101], v[100:101], 0.5, v[108:109] op_sel_hi:[1,0,1]
	v_lshlrev_b32_e32 v130, 16, v131
	v_pk_fma_f32 v[110:111], v[96:97], 0.5, v[128:129] op_sel_hi:[1,0,1]
	v_mul_f32_e32 v96, v101, v101
	v_mul_f32_e32 v97, v103, v103
	v_fmac_f32_e32 v96, v100, v100
	v_fmac_f32_e32 v97, v102, v102
	v_and_b32_e32 v131, 0xffff0000, v131
	v_add_f32_e32 v96, v96, v97
	v_mul_f32_e32 v97, v111, v111
	v_pk_fma_f32 v[108:109], v[98:99], 0.5, v[130:131] op_sel_hi:[1,0,1]
	v_fmac_f32_e32 v97, v110, v110
	v_add_f32_e32 v96, v97, v96
	v_mul_f32_e32 v97, v109, v109
	v_fmac_f32_e32 v97, v108, v108
	v_add_f32_e32 v96, v97, v96
	v_add_f32_e32 v96, v132, v96
	v_mov_b32_e32 v97, v96
	s_nop 1
	v_permlane16_swap_b32_e32 v96, v97
	v_cvt_pk_bf16_f32 v106, v106, v107
	v_cvt_pk_bf16_f32 v107, v126, v127
	global_store_dwordx4 v[152:153], v[104:107], off
	v_cvt_pk_bf16_f32 v98, v100, v101
	s_waitcnt lgkmcnt(0)
	v_add_f32_e32 v96, v96, v97
	v_mov_b32_e32 v97, v96
	s_nop 1
	v_permlane32_swap_b32_e32 v96, v97
	v_cvt_pk_bf16_f32 v99, v102, v103
	v_cvt_pk_bf16_f32 v100, v110, v111
	v_cvt_pk_bf16_f32 v101, v108, v109
	global_store_dwordx4 v[152:153], v[98:101], off offset:256
	s_and_saveexec_b64 s[22:23], s[6:7]
	s_cbranch_execz .LBB0_281
	v_lshlrev_b64 v[98:99], 6, v[150:151]
	v_lshl_add_u64 v[98:99], s[40:41], 0, v[98:99]
	v_lshl_add_u64 v[98:99], s[50:51], 2, v[98:99]
	s_lshl_b32 s68, s57, 2
	v_lshl_add_u64 v[98:99], v[98:99], 0, s[68:69]
	s_waitcnt lgkmcnt(0)
	v_add_f32_e32 v96, v96, v97
	global_store_dword v[98:99], v96, off
.LBB0_281:
	s_or_b64 exec, exec, s[22:23]
	v_or_b32_e32 v104, 48, v148
	v_ashrrev_i32_e32 v105, 31, v104
	s_waitcnt lgkmcnt(0)
	v_lshlrev_b64 v[96:97], 11, v[104:105]
	v_lshl_add_u64 v[96:97], s[18:19], 0, v[96:97]
	v_lshl_add_u64 v[106:107], v[146:147], 1, v[96:97]
	s_waitcnt vmcnt(14)
	s_waitcnt vmcnt(14)
	v_lshlrev_b32_e32 v108, 16, v172
	v_and_b32_e32 v109, 0xffff0000, v172
	v_lshlrev_b32_e32 v110, 16, v173
	v_and_b32_e32 v111, 0xffff0000, v173
	v_lshlrev_b32_e32 v116, 16, v174
	v_and_b32_e32 v117, 0xffff0000, v174
	v_lshlrev_b32_e32 v118, 16, v175
	v_and_b32_e32 v119, 0xffff0000, v175
	v_pk_fma_f32 v[94:95], v[94:95], 0.5, v[110:111] op_sel_hi:[1,0,1]
	v_pk_fma_f32 v[92:93], v[92:93], 0.5, v[108:109] op_sel_hi:[1,0,1]
	v_pk_fma_f32 v[108:109], v[90:91], 0.5, v[118:119] op_sel_hi:[1,0,1]
	v_pk_fma_f32 v[90:91], v[88:89], 0.5, v[116:117] op_sel_hi:[1,0,1]
	v_mul_f32_e32 v88, v93, v93
	v_mul_f32_e32 v89, v95, v95
	v_fmac_f32_e32 v88, v92, v92
	v_fmac_f32_e32 v89, v94, v94
	v_add_f32_e32 v88, v88, v89
	v_mul_f32_e32 v89, v91, v91
	v_fmac_f32_e32 v89, v90, v90
	v_add_f32_e32 v88, v89, v88
	v_mul_f32_e32 v89, v109, v109
	v_fmac_f32_e32 v89, v108, v108
	v_add_f32_e32 v116, v89, v88
	v_cvt_pk_bf16_f32 v88, v92, v93
	v_cvt_pk_bf16_f32 v89, v94, v95
	s_waitcnt vmcnt(14)
	v_lshlrev_b32_e32 v92, 16, v176
	v_and_b32_e32 v93, 0xffff0000, v176
	v_lshlrev_b32_e32 v94, 16, v177
	v_and_b32_e32 v95, 0xffff0000, v177
	v_lshlrev_b32_e32 v110, 16, v178
	v_and_b32_e32 v111, 0xffff0000, v178
	v_pk_fma_f32 v[86:87], v[86:87], 0.5, v[94:95] op_sel_hi:[1,0,1]
	v_pk_fma_f32 v[84:85], v[84:85], 0.5, v[92:93] op_sel_hi:[1,0,1]
	v_lshlrev_b32_e32 v112, 16, v179
	v_pk_fma_f32 v[94:95], v[80:81], 0.5, v[110:111] op_sel_hi:[1,0,1]
	v_mul_f32_e32 v80, v85, v85
	v_mul_f32_e32 v81, v87, v87
	v_fmac_f32_e32 v80, v84, v84
	v_fmac_f32_e32 v81, v86, v86
	v_and_b32_e32 v113, 0xffff0000, v179
	v_add_f32_e32 v80, v80, v81
	v_mul_f32_e32 v81, v95, v95
	v_pk_fma_f32 v[92:93], v[82:83], 0.5, v[112:113] op_sel_hi:[1,0,1]
	v_fmac_f32_e32 v81, v94, v94
	v_add_f32_e32 v80, v81, v80
	v_mul_f32_e32 v81, v93, v93
	v_fmac_f32_e32 v81, v92, v92
	v_add_f32_e32 v80, v81, v80
	v_add_f32_e32 v80, v116, v80
	v_mov_b32_e32 v81, v80
	s_nop 1
	v_permlane16_swap_b32_e32 v80, v81
	v_cvt_pk_bf16_f32 v90, v90, v91
	v_cvt_pk_bf16_f32 v91, v108, v109
	global_store_dwordx4 v[122:123], v[88:91], off
	v_cvt_pk_bf16_f32 v82, v84, v85
	s_waitcnt lgkmcnt(0)
	v_add_f32_e32 v80, v80, v81
	v_mov_b32_e32 v81, v80
	s_nop 1
	v_permlane32_swap_b32_e32 v80, v81
	v_cvt_pk_bf16_f32 v83, v86, v87
	v_cvt_pk_bf16_f32 v84, v94, v95
	v_cvt_pk_bf16_f32 v85, v92, v93
	global_store_dwordx4 v[122:123], v[82:85], off offset:256
	s_and_saveexec_b64 s[22:23], s[6:7]
	s_cbranch_execz .LBB0_283
	v_lshlrev_b64 v[82:83], 6, v[120:121]
	v_lshl_add_u64 v[82:83], s[40:41], 0, v[82:83]
	v_lshl_add_u64 v[82:83], s[50:51], 2, v[82:83]
	s_lshl_b32 s68, s57, 2
	v_lshl_add_u64 v[82:83], v[82:83], 0, s[68:69]
	s_waitcnt lgkmcnt(0)
	v_add_f32_e32 v80, v80, v81
	global_store_dword v[82:83], v80, off
; __device__ __forceinline__ unsigned cvt_pk_bf16(float lo, float hi) { unsigned r; asm volatile("v_cvt_pk_bf16_f32 %0, %1, %2" : "=v"(r) : "v"(lo), "v"(hi)); return r; }
; __device__ __forceinline__ float bflo(unsigned w) { return __uint_as_float(w << 16); }
; __device__ __forceinline__ float bfhi(unsigned w) { return __uint_as_float(w & 0xffff0000u); }
;     __device__ __forceinline__ void operator()(const f32x4 (&acc)[2][2][4][2], const Unit& u, int wr, int wc, int fr, int fq) const {
;     ...
; #pragma unroll
;         for (int g = 0; g < 8; ++g) { const int ai = g >> 2, m = g & 3; const int row = row0 + ai * HALF + m * 16; const size_t off = (size_t)row * 1024 + col0; float ss = 0.f;
;             if (g < 7) { const int g1 = g + 1; const size_t offn = (size_t)(row0 + (g1 >> 2) * HALF + (g1 & 3) * 16) * 1024 + col0;
; #pragma unroll
;                 for (int bj = 0; bj < 2; ++bj) nxt[bj] = *(const u32x4*)(xb + offn + bj * HALF); }
; #pragma unroll
;             for (int bj = 0; bj < 2; ++bj) { const u32x4 c = cur[bj];
;                 const f32x4 b0 = (f32x4){bflo(c[0]), bfhi(c[0]), bflo(c[1]), bfhi(c[1])}, b1 = (f32x4){bflo(c[2]), bfhi(c[2]), bflo(c[3]), bfhi(c[3])};
;                 const f32x4 v0 = b0 + (acc[ai][bj][m][0] + bv[bj][0]) * scale, v1 = b1 + (acc[ai][bj][m][1] + bv[bj][1]) * scale;
;                 ss += (v0[0] * v0[0] + v0[1] * v0[1]) + (v0[2] * v0[2] + v0[3] * v0[3]) + (v1[0] * v1[0] + v1[1] * v1[1]) + (v1[2] * v1[2] + v1[3] * v1[3]);
;                 u32x4 w; w.x = cvt_pk_bf16(v0[0], v0[1]); w.y = cvt_pk_bf16(v0[2], v0[3]); w.z = cvt_pk_bf16(v1[0], v1[1]); w.w = cvt_pk_bf16(v1[2], v1[3]);
;                 *(u32x4*)(xb + off + bj * HALF) = w; }
;             ss += __shfl_xor(ss, 16); ss += __shfl_xor(ss, 32);
;             if (fq == 0) partn[(size_t)row * 16 + u.pn * 4 + wc] = ss;
.LBB0_283:
	s_or_b64 exec, exec, s[22:23]
	v_add_u32_e32 v88, 0x80, v148
	v_ashrrev_i32_e32 v89, 31, v88
	s_waitcnt lgkmcnt(0)
	v_lshlrev_b64 v[80:81], 11, v[88:89]
	v_lshl_add_u64 v[80:81], s[18:19], 0, v[80:81]
	v_lshl_add_u64 v[90:91], v[146:147], 1, v[80:81]
	s_waitcnt vmcnt(14)
	s_waitcnt vmcnt(14)
	v_lshlrev_b32_e32 v92, 16, v186
	v_and_b32_e32 v93, 0xffff0000, v186
	v_lshlrev_b32_e32 v94, 16, v187
	v_and_b32_e32 v95, 0xffff0000, v187
	v_lshlrev_b32_e32 v100, 16, v188
	v_and_b32_e32 v101, 0xffff0000, v188
	v_lshlrev_b32_e32 v102, 16, v189
	v_and_b32_e32 v103, 0xffff0000, v189
	v_pk_fma_f32 v[78:79], v[78:79], 0.5, v[94:95] op_sel_hi:[1,0,1]
	v_pk_fma_f32 v[76:77], v[76:77], 0.5, v[92:93] op_sel_hi:[1,0,1]
	v_pk_fma_f32 v[92:93], v[74:75], 0.5, v[102:103] op_sel_hi:[1,0,1]
	v_pk_fma_f32 v[74:75], v[72:73], 0.5, v[100:101] op_sel_hi:[1,0,1]
	v_mul_f32_e32 v72, v77, v77
	v_mul_f32_e32 v73, v79, v79
	v_fmac_f32_e32 v72, v76, v76
	v_fmac_f32_e32 v73, v78, v78
	v_add_f32_e32 v72, v72, v73
	v_mul_f32_e32 v73, v75, v75
	v_fmac_f32_e32 v73, v74, v74
	v_add_f32_e32 v72, v73, v72
	v_mul_f32_e32 v73, v93, v93
	v_fmac_f32_e32 v73, v92, v92
	v_add_f32_e32 v100, v73, v72
	v_cvt_pk_bf16_f32 v72, v76, v77
	v_cvt_pk_bf16_f32 v73, v78, v79
	s_waitcnt vmcnt(14)
	v_lshlrev_b32_e32 v76, 16, v190
	v_and_b32_e32 v77, 0xffff0000, v190
	v_lshlrev_b32_e32 v78, 16, v191
	v_and_b32_e32 v79, 0xffff0000, v191
	v_lshlrev_b32_e32 v94, 16, v192
	v_and_b32_e32 v95, 0xffff0000, v192
	v_pk_fma_f32 v[70:71], v[70:71], 0.5, v[78:79] op_sel_hi:[1,0,1]
	v_pk_fma_f32 v[68:69], v[68:69], 0.5, v[76:77] op_sel_hi:[1,0,1]
	v_lshlrev_b32_e32 v96, 16, v193
	v_pk_fma_f32 v[78:79], v[64:65], 0.5, v[94:95] op_sel_hi:[1,0,1]
	v_mul_f32_e32 v64, v69, v69
	v_mul_f32_e32 v65, v71, v71
	v_fmac_f32_e32 v64, v68, v68
	v_fmac_f32_e32 v65, v70, v70
	v_and_b32_e32 v97, 0xffff0000, v193
	v_add_f32_e32 v64, v64, v65
	v_mul_f32_e32 v65, v79, v79
	v_pk_fma_f32 v[76:77], v[66:67], 0.5, v[96:97] op_sel_hi:[1,0,1]
	v_fmac_f32_e32 v65, v78, v78
	v_add_f32_e32 v64, v65, v64
	v_mul_f32_e32 v65, v77, v77
	v_fmac_f32_e32 v65, v76, v76
	v_add_f32_e32 v64, v65, v64
	v_add_f32_e32 v64, v100, v64
	v_mov_b32_e32 v65, v64
	s_nop 1
	v_permlane16_swap_b32_e32 v64, v65
	v_cvt_pk_bf16_f32 v74, v74, v75
	v_cvt_pk_bf16_f32 v75, v92, v93
	global_store_dwordx4 v[106:107], v[72:75], off
	v_cvt_pk_bf16_f32 v66, v68, v69
	s_waitcnt lgkmcnt(0)
	v_add_f32_e32 v64, v64, v65
	v_mov_b32_e32 v65, v64
	s_nop 1
	v_permlane32_swap_b32_e32 v64, v65
	v_cvt_pk_bf16_f32 v67, v70, v71
	v_cvt_pk_bf16_f32 v68, v78, v79
	v_cvt_pk_bf16_f32 v69, v76, v77
	global_store_dwordx4 v[106:107], v[66:69], off offset:256
	s_and_saveexec_b64 s[22:23], s[6:7]
	s_cbranch_execz .LBB0_285
	v_lshlrev_b64 v[66:67], 6, v[104:105]
	v_lshl_add_u64 v[66:67], s[40:41], 0, v[66:67]
	v_lshl_add_u64 v[66:67], s[50:51], 2, v[66:67]
	s_lshl_b32 s68, s57, 2
	v_lshl_add_u64 v[66:67], v[66:67], 0, s[68:69]
	s_waitcnt lgkmcnt(0)
	v_add_f32_e32 v64, v64, v65
	global_store_dword v[66:67], v64, off
.LBB0_285:
	s_or_b64 exec, exec, s[22:23]
	v_or_b32_e32 v72, 16, v88
	v_ashrrev_i32_e32 v73, 31, v72
	s_waitcnt lgkmcnt(0)
	v_lshlrev_b64 v[64:65], 11, v[72:73]
	v_lshl_add_u64 v[64:65], s[18:19], 0, v[64:65]
	v_lshl_add_u64 v[74:75], v[146:147], 1, v[64:65]
	s_waitcnt vmcnt(14)
	s_waitcnt vmcnt(14)
	v_lshlrev_b32_e32 v76, 16, v194
	v_and_b32_e32 v77, 0xffff0000, v194
	v_lshlrev_b32_e32 v78, 16, v195
	v_and_b32_e32 v79, 0xffff0000, v195
	v_lshlrev_b32_e32 v84, 16, v196
	v_and_b32_e32 v85, 0xffff0000, v196
	v_lshlrev_b32_e32 v86, 16, v197
	v_and_b32_e32 v87, 0xffff0000, v197
	v_pk_fma_f32 v[62:63], v[62:63], 0.5, v[78:79] op_sel_hi:[1,0,1]
	v_pk_fma_f32 v[60:61], v[60:61], 0.5, v[76:77] op_sel_hi:[1,0,1]
	v_pk_fma_f32 v[76:77], v[58:59], 0.5, v[86:87] op_sel_hi:[1,0,1]
	v_pk_fma_f32 v[58:59], v[56:57], 0.5, v[84:85] op_sel_hi:[1,0,1]
	v_mul_f32_e32 v56, v61, v61
	v_mul_f32_e32 v57, v63, v63
	v_fmac_f32_e32 v56, v60, v60
	v_fmac_f32_e32 v57, v62, v62
	v_add_f32_e32 v56, v56, v57
	v_mul_f32_e32 v57, v59, v59
	v_fmac_f32_e32 v57, v58, v58
	v_add_f32_e32 v56, v57, v56
	v_mul_f32_e32 v57, v77, v77
	v_fmac_f32_e32 v57, v76, v76
	v_add_f32_e32 v84, v57, v56
	v_cvt_pk_bf16_f32 v56, v60, v61
	v_cvt_pk_bf16_f32 v57, v62, v63
	s_waitcnt vmcnt(14)
	v_lshlrev_b32_e32 v60, 16, v198
	v_and_b32_e32 v61, 0xffff0000, v198
	v_lshlrev_b32_e32 v62, 16, v199
	v_and_b32_e32 v63, 0xffff0000, v199
	v_lshlrev_b32_e32 v78, 16, v200
	v_and_b32_e32 v79, 0xffff0000, v200
	v_pk_fma_f32 v[54:55], v[54:55], 0.5, v[62:63] op_sel_hi:[1,0,1]
	v_pk_fma_f32 v[52:53], v[52:53], 0.5, v[60:61] op_sel_hi:[1,0,1]
	v_lshlrev_b32_e32 v80, 16, v201
	v_pk_fma_f32 v[62:63], v[48:49], 0.5, v[78:79] op_sel_hi:[1,0,1]
	v_mul_f32_e32 v48, v53, v53
	v_mul_f32_e32 v49, v55, v55
	v_fmac_f32_e32 v48, v52, v52
	v_fmac_f32_e32 v49, v54, v54
	v_and_b32_e32 v81, 0xffff0000, v201
	v_add_f32_e32 v48, v48, v49
	v_mul_f32_e32 v49, v63, v63
	v_pk_fma_f32 v[60:61], v[50:51], 0.5, v[80:81] op_sel_hi:[1,0,1]
	v_fmac_f32_e32 v49, v62, v62
	v_add_f32_e32 v48, v49, v48
	v_mul_f32_e32 v49, v61, v61
	v_fmac_f32_e32 v49, v60, v60
	v_add_f32_e32 v48, v49, v48
	v_add_f32_e32 v48, v84, v48
	v_mov_b32_e32 v49, v48
	s_nop 1
	v_permlane16_swap_b32_e32 v48, v49
	v_cvt_pk_bf16_f32 v58, v58, v59
	v_cvt_pk_bf16_f32 v59, v76, v77
	global_store_dwordx4 v[90:91], v[56:59], off
	v_cvt_pk_bf16_f32 v50, v52, v53
	s_waitcnt lgkmcnt(0)
	v_add_f32_e32 v48, v48, v49
	v_mov_b32_e32 v49, v48
	s_nop 1
	v_permlane32_swap_b32_e32 v48, v49
	v_cvt_pk_bf16_f32 v51, v54, v55
	v_cvt_pk_bf16_f32 v52, v62, v63
	v_cvt_pk_bf16_f32 v53, v60, v61
	global_store_dwordx4 v[90:91], v[50:53], off offset:256
	s_and_saveexec_b64 s[22:23], s[6:7]
	s_cbranch_execz .LBB0_287
	v_lshlrev_b64 v[50:51], 6, v[88:89]
	v_lshl_add_u64 v[50:51], s[40:41], 0, v[50:51]
	v_lshl_add_u64 v[50:51], s[50:51], 2, v[50:51]
	s_lshl_b32 s68, s57, 2
	v_lshl_add_u64 v[50:51], v[50:51], 0, s[68:69]
	s_waitcnt lgkmcnt(0)
	v_add_f32_e32 v48, v48, v49
	global_store_dword v[50:51], v48, off
; __device__ __forceinline__ unsigned cvt_pk_bf16(float lo, float hi) { unsigned r; asm volatile("v_cvt_pk_bf16_f32 %0, %1, %2" : "=v"(r) : "v"(lo), "v"(hi)); return r; }
; __device__ __forceinline__ float bflo(unsigned w) { return __uint_as_float(w << 16); }
; __device__ __forceinline__ float bfhi(unsigned w) { return __uint_as_float(w & 0xffff0000u); }
;     __device__ __forceinline__ void operator()(const f32x4 (&acc)[2][2][4][2], const Unit& u, int wr, int wc, int fr, int fq) const {
;     ...
; #pragma unroll
;         for (int g = 0; g < 8; ++g) { const int ai = g >> 2, m = g & 3; const int row = row0 + ai * HALF + m * 16; const size_t off = (size_t)row * 1024 + col0; float ss = 0.f;
;             if (g < 7) { const int g1 = g + 1; const size_t offn = (size_t)(row0 + (g1 >> 2) * HALF + (g1 & 3) * 16) * 1024 + col0;
; #pragma unroll
;                 for (int bj = 0; bj < 2; ++bj) nxt[bj] = *(const u32x4*)(xb + offn + bj * HALF); }
; #pragma unroll
;             for (int bj = 0; bj < 2; ++bj) { const u32x4 c = cur[bj];
;                 const f32x4 b0 = (f32x4){bflo(c[0]), bfhi(c[0]), bflo(c[1]), bfhi(c[1])}, b1 = (f32x4){bflo(c[2]), bfhi(c[2]), bflo(c[3]), bfhi(c[3])};
;                 const f32x4 v0 = b0 + (acc[ai][bj][m][0] + bv[bj][0]) * scale, v1 = b1 + (acc[ai][bj][m][1] + bv[bj][1]) * scale;
;                 ss += (v0[0] * v0[0] + v0[1] * v0[1]) + (v0[2] * v0[2] + v0[3] * v0[3]) + (v1[0] * v1[0] + v1[1] * v1[1]) + (v1[2] * v1[2] + v1[3] * v1[3]);
;                 u32x4 w; w.x = cvt_pk_bf16(v0[0], v0[1]); w.y = cvt_pk_bf16(v0[2], v0[3]); w.z = cvt_pk_bf16(v1[0], v1[1]); w.w = cvt_pk_bf16(v1[2], v1[3]);
;                 *(u32x4*)(xb + off + bj * HALF) = w; }
;             ss += __shfl_xor(ss, 16); ss += __shfl_xor(ss, 32);
;             if (fq == 0) partn[(size_t)row * 16 + u.pn * 4 + wc] = ss;
.LBB0_287:
	s_or_b64 exec, exec, s[22:23]
	v_or_b32_e32 v56, 32, v88
	v_ashrrev_i32_e32 v57, 31, v56
	s_waitcnt lgkmcnt(0)
	v_lshlrev_b64 v[48:49], 11, v[56:57]
	v_lshl_add_u64 v[48:49], s[18:19], 0, v[48:49]
	v_lshl_add_u64 v[58:59], v[146:147], 1, v[48:49]
	s_waitcnt vmcnt(14)
	s_waitcnt vmcnt(14)
	v_lshlrev_b32_e32 v60, 16, v216
	v_and_b32_e32 v61, 0xffff0000, v216
	v_lshlrev_b32_e32 v62, 16, v217
	v_and_b32_e32 v63, 0xffff0000, v217
	v_lshlrev_b32_e32 v68, 16, v218
	v_and_b32_e32 v69, 0xffff0000, v218
	v_lshlrev_b32_e32 v70, 16, v219
	v_and_b32_e32 v71, 0xffff0000, v219
	v_pk_fma_f32 v[46:47], v[46:47], 0.5, v[62:63] op_sel_hi:[1,0,1]
	v_pk_fma_f32 v[44:45], v[44:45], 0.5, v[60:61] op_sel_hi:[1,0,1]
	v_pk_fma_f32 v[60:61], v[42:43], 0.5, v[70:71] op_sel_hi:[1,0,1]
	v_pk_fma_f32 v[42:43], v[40:41], 0.5, v[68:69] op_sel_hi:[1,0,1]
	v_mul_f32_e32 v40, v45, v45
	v_mul_f32_e32 v41, v47, v47
	v_fmac_f32_e32 v40, v44, v44
	v_fmac_f32_e32 v41, v46, v46
	v_add_f32_e32 v40, v40, v41
	v_mul_f32_e32 v41, v43, v43
	v_fmac_f32_e32 v41, v42, v42
	v_add_f32_e32 v40, v41, v40
	v_mul_f32_e32 v41, v61, v61
	v_fmac_f32_e32 v41, v60, v60
	v_add_f32_e32 v68, v41, v40
	v_cvt_pk_bf16_f32 v40, v44, v45
	v_cvt_pk_bf16_f32 v41, v46, v47
	s_waitcnt vmcnt(14)
	v_lshlrev_b32_e32 v44, 16, v224
	v_and_b32_e32 v45, 0xffff0000, v224
	v_lshlrev_b32_e32 v46, 16, v225
	v_and_b32_e32 v47, 0xffff0000, v225
	v_lshlrev_b32_e32 v62, 16, v226
	v_and_b32_e32 v63, 0xffff0000, v226
	v_pk_fma_f32 v[38:39], v[38:39], 0.5, v[46:47] op_sel_hi:[1,0,1]
	v_pk_fma_f32 v[36:37], v[36:37], 0.5, v[44:45] op_sel_hi:[1,0,1]
	v_lshlrev_b32_e32 v64, 16, v227
	v_pk_fma_f32 v[46:47], v[32:33], 0.5, v[62:63] op_sel_hi:[1,0,1]
	v_mul_f32_e32 v32, v37, v37
	v_mul_f32_e32 v33, v39, v39
	v_fmac_f32_e32 v32, v36, v36
	v_fmac_f32_e32 v33, v38, v38
	v_and_b32_e32 v65, 0xffff0000, v227
	v_add_f32_e32 v32, v32, v33
	v_mul_f32_e32 v33, v47, v47
	v_pk_fma_f32 v[44:45], v[34:35], 0.5, v[64:65] op_sel_hi:[1,0,1]
	v_fmac_f32_e32 v33, v46, v46
	v_add_f32_e32 v32, v33, v32
	v_mul_f32_e32 v33, v45, v45
	v_fmac_f32_e32 v33, v44, v44
	v_add_f32_e32 v32, v33, v32
	v_add_f32_e32 v32, v68, v32
	v_mov_b32_e32 v33, v32
	s_nop 1
	v_permlane16_swap_b32_e32 v32, v33
	v_cvt_pk_bf16_f32 v42, v42, v43
	v_cvt_pk_bf16_f32 v43, v60, v61
	global_store_dwordx4 v[74:75], v[40:43], off
	v_cvt_pk_bf16_f32 v34, v36, v37
	s_waitcnt lgkmcnt(0)
	v_add_f32_e32 v32, v32, v33
	v_mov_b32_e32 v33, v32
	s_nop 1
	v_permlane32_swap_b32_e32 v32, v33
	v_cvt_pk_bf16_f32 v35, v38, v39
	v_cvt_pk_bf16_f32 v36, v46, v47
	v_cvt_pk_bf16_f32 v37, v44, v45
	global_store_dwordx4 v[74:75], v[34:37], off offset:256
	s_and_saveexec_b64 s[22:23], s[6:7]
	s_cbranch_execz .LBB0_289
	v_lshlrev_b64 v[34:35], 6, v[72:73]
	v_lshl_add_u64 v[34:35], s[40:41], 0, v[34:35]
	v_lshl_add_u64 v[34:35], s[50:51], 2, v[34:35]
	s_lshl_b32 s68, s57, 2
	v_lshl_add_u64 v[34:35], v[34:35], 0, s[68:69]
	s_waitcnt lgkmcnt(0)
	v_add_f32_e32 v32, v32, v33
	global_store_dword v[34:35], v32, off
; __device__ __forceinline__ unsigned cvt_pk_bf16(float lo, float hi) { unsigned r; asm volatile("v_cvt_pk_bf16_f32 %0, %1, %2" : "=v"(r) : "v"(lo), "v"(hi)); return r; }
; __device__ __forceinline__ float bflo(unsigned w) { return __uint_as_float(w << 16); }
; __device__ __forceinline__ float bfhi(unsigned w) { return __uint_as_float(w & 0xffff0000u); }
;     __device__ __forceinline__ void operator()(const f32x4 (&acc)[2][2][4][2], const Unit& u, int wr, int wc, int fr, int fq) const {
;     ...
; #pragma unroll
;         for (int g = 0; g < 8; ++g) { const int ai = g >> 2, m = g & 3; const int row = row0 + ai * HALF + m * 16; const size_t off = (size_t)row * 1024 + col0; float ss = 0.f;
;             if (g < 7) { const int g1 = g + 1; const size_t offn = (size_t)(row0 + (g1 >> 2) * HALF + (g1 & 3) * 16) * 1024 + col0;
; #pragma unroll
;                 for (int bj = 0; bj < 2; ++bj) nxt[bj] = *(const u32x4*)(xb + offn + bj * HALF); }
; #pragma unroll
;             for (int bj = 0; bj < 2; ++bj) { const u32x4 c = cur[bj];
;                 const f32x4 b0 = (f32x4){bflo(c[0]), bfhi(c[0]), bflo(c[1]), bfhi(c[1])}, b1 = (f32x4){bflo(c[2]), bfhi(c[2]), bflo(c[3]), bfhi(c[3])};
;                 const f32x4 v0 = b0 + (acc[ai][bj][m][0] + bv[bj][0]) * scale, v1 = b1 + (acc[ai][bj][m][1] + bv[bj][1]) * scale;
;                 ss += (v0[0] * v0[0] + v0[1] * v0[1]) + (v0[2] * v0[2] + v0[3] * v0[3]) + (v1[0] * v1[0] + v1[1] * v1[1]) + (v1[2] * v1[2] + v1[3] * v1[3]);
;                 u32x4 w; w.x = cvt_pk_bf16(v0[0], v0[1]); w.y = cvt_pk_bf16(v0[2], v0[3]); w.z = cvt_pk_bf16(v1[0], v1[1]); w.w = cvt_pk_bf16(v1[2], v1[3]);
;                 *(u32x4*)(xb + off + bj * HALF) = w; }
;             ss += __shfl_xor(ss, 16); ss += __shfl_xor(ss, 32);
;             if (fq == 0) partn[(size_t)row * 16 + u.pn * 4 + wc] = ss;
.LBB0_289:
	s_or_b64 exec, exec, s[22:23]
	v_or_b32_e32 v40, 48, v88
	v_ashrrev_i32_e32 v41, 31, v40
	s_waitcnt lgkmcnt(0)
	v_lshlrev_b64 v[32:33], 11, v[40:41]
	v_lshl_add_u64 v[32:33], s[18:19], 0, v[32:33]
	v_lshl_add_u64 v[42:43], v[146:147], 1, v[32:33]
	s_waitcnt vmcnt(14)
	s_waitcnt vmcnt(14)
	v_lshlrev_b32_e32 v44, 16, v230
	v_and_b32_e32 v45, 0xffff0000, v230
	v_lshlrev_b32_e32 v46, 16, v231
	v_and_b32_e32 v47, 0xffff0000, v231
	v_lshlrev_b32_e32 v52, 16, v232
	v_and_b32_e32 v53, 0xffff0000, v232
	v_lshlrev_b32_e32 v54, 16, v233
	v_and_b32_e32 v55, 0xffff0000, v233
	v_pk_fma_f32 v[30:31], v[30:31], 0.5, v[46:47] op_sel_hi:[1,0,1]
	v_pk_fma_f32 v[28:29], v[28:29], 0.5, v[44:45] op_sel_hi:[1,0,1]
	v_pk_fma_f32 v[44:45], v[26:27], 0.5, v[54:55] op_sel_hi:[1,0,1]
	v_pk_fma_f32 v[26:27], v[24:25], 0.5, v[52:53] op_sel_hi:[1,0,1]
	v_mul_f32_e32 v24, v29, v29
	v_mul_f32_e32 v25, v31, v31
	v_fmac_f32_e32 v24, v28, v28
	v_fmac_f32_e32 v25, v30, v30
	v_add_f32_e32 v24, v24, v25
	v_mul_f32_e32 v25, v27, v27
	v_fmac_f32_e32 v25, v26, v26
	v_add_f32_e32 v24, v25, v24
	v_mul_f32_e32 v25, v45, v45
	v_fmac_f32_e32 v25, v44, v44
	v_add_f32_e32 v52, v25, v24
	v_cvt_pk_bf16_f32 v24, v28, v29
	v_cvt_pk_bf16_f32 v25, v30, v31
	s_waitcnt vmcnt(14)
	v_lshlrev_b32_e32 v28, 16, v238
	v_and_b32_e32 v29, 0xffff0000, v238
	v_lshlrev_b32_e32 v30, 16, v239
	v_and_b32_e32 v31, 0xffff0000, v239
	v_lshlrev_b32_e32 v46, 16, v240
	v_and_b32_e32 v47, 0xffff0000, v240
	v_pk_fma_f32 v[22:23], v[22:23], 0.5, v[30:31] op_sel_hi:[1,0,1]
	v_pk_fma_f32 v[20:21], v[20:21], 0.5, v[28:29] op_sel_hi:[1,0,1]
	v_lshlrev_b32_e32 v48, 16, v241
	v_pk_fma_f32 v[30:31], v[16:17], 0.5, v[46:47] op_sel_hi:[1,0,1]
	v_mul_f32_e32 v16, v21, v21
	v_mul_f32_e32 v17, v23, v23
	v_fmac_f32_e32 v16, v20, v20
	v_fmac_f32_e32 v17, v22, v22
	v_and_b32_e32 v49, 0xffff0000, v241
	v_add_f32_e32 v16, v16, v17
	v_mul_f32_e32 v17, v31, v31
	v_pk_fma_f32 v[28:29], v[18:19], 0.5, v[48:49] op_sel_hi:[1,0,1]
	v_fmac_f32_e32 v17, v30, v30
	v_add_f32_e32 v16, v17, v16
	v_mul_f32_e32 v17, v29, v29
	v_fmac_f32_e32 v17, v28, v28
	v_add_f32_e32 v16, v17, v16
	v_add_f32_e32 v16, v52, v16
	v_mov_b32_e32 v17, v16
	s_nop 1
	v_permlane16_swap_b32_e32 v16, v17
	v_cvt_pk_bf16_f32 v26, v26, v27
	v_cvt_pk_bf16_f32 v27, v44, v45
	global_store_dwordx4 v[58:59], v[24:27], off
	v_cvt_pk_bf16_f32 v18, v20, v21
	s_waitcnt lgkmcnt(0)
	v_add_f32_e32 v16, v16, v17
	v_mov_b32_e32 v17, v16
	s_nop 1
	v_permlane32_swap_b32_e32 v16, v17
	v_cvt_pk_bf16_f32 v19, v22, v23
	v_cvt_pk_bf16_f32 v20, v30, v31
	v_cvt_pk_bf16_f32 v21, v28, v29
	global_store_dwordx4 v[58:59], v[18:21], off offset:256
	s_and_saveexec_b64 s[22:23], s[6:7]
	s_cbranch_execz .LBB0_291
	v_lshlrev_b64 v[18:19], 6, v[56:57]
	v_lshl_add_u64 v[18:19], s[40:41], 0, v[18:19]
	v_lshl_add_u64 v[18:19], s[50:51], 2, v[18:19]
	s_lshl_b32 s68, s57, 2
	v_lshl_add_u64 v[18:19], v[18:19], 0, s[68:69]
	s_waitcnt lgkmcnt(0)
	v_add_f32_e32 v16, v16, v17
	global_store_dword v[18:19], v16, off
.LBB0_291:
	s_or_b64 exec, exec, s[22:23]
	s_waitcnt vmcnt(14)
	v_lshlrev_b32_e32 v16, 16, v242
	s_waitcnt lgkmcnt(0)
	v_and_b32_e32 v17, 0xffff0000, v242
	v_lshlrev_b32_e32 v18, 16, v243
	v_and_b32_e32 v19, 0xffff0000, v243
	v_lshlrev_b32_e32 v20, 16, v244
	v_and_b32_e32 v21, 0xffff0000, v244
	v_lshlrev_b32_e32 v22, 16, v245
	v_and_b32_e32 v23, 0xffff0000, v245
	v_pk_fma_f32 v[14:15], v[14:15], 0.5, v[18:19] op_sel_hi:[1,0,1]
	v_pk_fma_f32 v[12:13], v[12:13], 0.5, v[16:17] op_sel_hi:[1,0,1]
	v_pk_fma_f32 v[16:17], v[10:11], 0.5, v[22:23] op_sel_hi:[1,0,1]
	v_pk_fma_f32 v[10:11], v[8:9], 0.5, v[20:21] op_sel_hi:[1,0,1]
	v_mul_f32_e32 v8, v13, v13
	v_mul_f32_e32 v9, v15, v15
	v_fmac_f32_e32 v8, v12, v12
	v_fmac_f32_e32 v9, v14, v14
	v_add_f32_e32 v8, v8, v9
	v_mul_f32_e32 v9, v11, v11
	v_fmac_f32_e32 v9, v10, v10
	v_add_f32_e32 v8, v9, v8
	v_mul_f32_e32 v9, v17, v17
	v_fmac_f32_e32 v9, v16, v16
	v_add_f32_e32 v22, v9, v8
	v_cvt_pk_bf16_f32 v8, v12, v13
	v_cvt_pk_bf16_f32 v9, v14, v15
	s_waitcnt vmcnt(14)
	v_lshlrev_b32_e32 v12, 16, v246
	v_and_b32_e32 v13, 0xffff0000, v246
	v_lshlrev_b32_e32 v14, 16, v247
	v_and_b32_e32 v15, 0xffff0000, v247
	v_lshlrev_b32_e32 v18, 16, v248
	v_and_b32_e32 v19, 0xffff0000, v248
	v_pk_fma_f32 v[6:7], v[6:7], 0.5, v[14:15] op_sel_hi:[1,0,1]
	v_pk_fma_f32 v[4:5], v[4:5], 0.5, v[12:13] op_sel_hi:[1,0,1]
	v_lshlrev_b32_e32 v20, 16, v249
	v_pk_fma_f32 v[14:15], v[0:1], 0.5, v[18:19] op_sel_hi:[1,0,1]
	v_mul_f32_e32 v0, v5, v5
	v_mul_f32_e32 v1, v7, v7
	v_fmac_f32_e32 v0, v4, v4
	v_fmac_f32_e32 v1, v6, v6
	v_and_b32_e32 v21, 0xffff0000, v249
	v_add_f32_e32 v0, v0, v1
	v_mul_f32_e32 v1, v15, v15
	v_pk_fma_f32 v[12:13], v[2:3], 0.5, v[20:21] op_sel_hi:[1,0,1]
	v_fmac_f32_e32 v1, v14, v14
	v_add_f32_e32 v0, v1, v0
	v_mul_f32_e32 v1, v13, v13
	v_fmac_f32_e32 v1, v12, v12
	v_add_f32_e32 v0, v1, v0
	v_add_f32_e32 v0, v22, v0
	v_mov_b32_e32 v1, v0
	s_nop 1
	v_permlane16_swap_b32_e32 v0, v1
	v_cvt_pk_bf16_f32 v10, v10, v11
	v_cvt_pk_bf16_f32 v11, v16, v17
	global_store_dwordx4 v[42:43], v[8:11], off
	v_cvt_pk_bf16_f32 v2, v4, v5
	s_waitcnt lgkmcnt(0)
	v_add_f32_e32 v0, v0, v1
	v_mov_b32_e32 v1, v0
	s_nop 1
	v_permlane32_swap_b32_e32 v0, v1
	v_cvt_pk_bf16_f32 v3, v6, v7
	v_cvt_pk_bf16_f32 v4, v14, v15
	v_cvt_pk_bf16_f32 v5, v12, v13
	global_store_dwordx4 v[42:43], v[2:5], off offset:256
	s_and_saveexec_b64 s[22:23], s[6:7]
	s_cbranch_execz .LBB0_293
	v_lshlrev_b64 v[2:3], 6, v[40:41]
	v_lshl_add_u64 v[2:3], s[40:41], 0, v[2:3]
	v_lshl_add_u64 v[2:3], s[50:51], 2, v[2:3]
	s_lshl_b32 s68, s57, 2
	v_lshl_add_u64 v[2:3], v[2:3], 0, s[68:69]
	s_waitcnt lgkmcnt(0)
	v_add_f32_e32 v0, v0, v1
	global_store_dword v[2:3], v0, off

; __device__ __forceinline__ unsigned cvt_pk_bf16(float lo, float hi) { unsigned r; asm volatile("v_cvt_pk_bf16_f32 %0, %1, %2" : "=v"(r) : "v"(lo), "v"(hi)); return r; }
; __device__ __forceinline__ float bflo(unsigned w) { return __uint_as_float(w << 16); }
; __device__ __forceinline__ float bfhi(unsigned w) { return __uint_as_float(w & 0xffff0000u); }
;     __device__ __forceinline__ void operator()(const f32x4 (&acc)[2][2][4][2], const Unit& u, int wr, int wc, int fr, int fq) const {
;         const int row0 = u.pm * BM + wr * 64 + fr, col0 = u.pn * BM + wc * 32 + 8 * fq;
;         f32x4 bv[2][2];
; #pragma unroll
;         for (int bj = 0; bj < 2; ++bj)
; #pragma unroll
;             for (int n = 0; n < 2; ++n) bv[bj][n] = bias ? *(const f32x4*)(bias + col0 + bj * HALF + 4 * n) : (f32x4){0.f, 0.f, 0.f, 0.f};
;         u32x4 cur[2], nxt[2];
;         { const size_t off = (size_t)row0 * 1024 + col0;
; #pragma unroll
;           for (int bj = 0; bj < 2; ++bj) cur[bj] = *(const u32x4*)(xb + off + bj * HALF); }
; #pragma unroll
;         for (int g = 0; g < 8; ++g) { const int ai = g >> 2, m = g & 3; const int row = row0 + ai * HALF + m * 16; const size_t off = (size_t)row * 1024 + col0; float ss = 0.f;
;             if (g < 7) { const int g1 = g + 1; const size_t offn = (size_t)(row0 + (g1 >> 2) * HALF + (g1 & 3) * 16) * 1024 + col0;
; #pragma unroll
;                 for (int bj = 0; bj < 2; ++bj) nxt[bj] = *(const u32x4*)(xb + offn + bj * HALF); }
; #pragma unroll
;             for (int bj = 0; bj < 2; ++bj) { const u32x4 c = cur[bj];
;                 const f32x4 b0 = (f32x4){bflo(c[0]), bfhi(c[0]), bflo(c[1]), bfhi(c[1])}, b1 = (f32x4){bflo(c[2]), bfhi(c[2]), bflo(c[3]), bfhi(c[3])};
;                 const f32x4 v0 = b0 + (acc[ai][bj][m][0] + bv[bj][0]) * scale, v1 = b1 + (acc[ai][bj][m][1] + bv[bj][1]) * scale;
;                 ss += (v0[0] * v0[0] + v0[1] * v0[1]) + (v0[2] * v0[2] + v0[3] * v0[3]) + (v1[0] * v1[0] + v1[1] * v1[1]) + (v1[2] * v1[2] + v1[3] * v1[3]);
;                 u32x4 w; w.x = cvt_pk_bf16(v0[0], v0[1]); w.y = cvt_pk_bf16(v0[2], v0[3]); w.z = cvt_pk_bf16(v1[0], v1[1]); w.w = cvt_pk_bf16(v1[2], v1[3]);
;                 *(u32x4*)(xb + off + bj * HALF) = w; }
;             ss += __shfl_xor(ss, 16); ss += __shfl_xor(ss, 32);
;             if (fq == 0) partn[(size_t)row * 16 + u.pn * 4 + wc] = ss;
.LBB0_910:
	v_lshl_add_u32 v164, s62, 8, v172
	v_ashrrev_i32_e32 v165, 31, v164
	v_lshlrev_b64 v[144:145], 11, v[164:165]
	v_lshl_add_u64 v[144:145], s[18:19], 0, v[144:145]
	v_lshlrev_b64 v[146:147], 1, v[162:163]
	v_lshl_add_u64 v[170:171], v[144:145], 0, v[146:147]
	global_load_dwordx4 v[176:179], v[170:171], off
	global_load_dwordx4 v[186:189], v[170:171], off offset:256
	v_or_b32_e32 v166, 16, v164
	v_ashrrev_i32_e32 v167, 31, v166
	v_lshlrev_b64 v[144:145], 11, v[166:167]
	v_lshl_add_u64 v[144:145], s[18:19], 0, v[144:145]
	v_lshl_add_u64 v[168:169], v[144:145], 0, v[146:147]
	global_load_dwordx4 v[148:151], v[168:169], off
	global_load_dwordx4 v[144:147], v[168:169], off offset:256
	s_waitcnt vmcnt(0)
	v_pk_add_f32 v[142:143], v[142:143], v[102:103]
	v_pk_add_f32 v[140:141], v[140:141], v[100:101]
	v_pk_add_f32 v[138:139], v[138:139], v[94:95]
	v_pk_add_f32 v[136:137], v[136:137], v[92:93]
	v_pk_add_f32 v[134:135], v[134:135], v[90:91]
	v_pk_add_f32 v[132:133], v[132:133], v[88:89]
	v_pk_add_f32 v[130:131], v[130:131], v[86:87]
	v_pk_add_f32 v[128:129], v[128:129], v[84:85]
	s_lshl_b32 s8, s3, 2
	s_ashr_i32 s9, s8, 31
	v_lshlrev_b32_e32 v190, 16, v176
	v_and_b32_e32 v191, 0xffff0000, v176
	v_lshlrev_b32_e32 v176, 16, v177
	v_and_b32_e32 v177, 0xffff0000, v177
	v_lshlrev_b32_e32 v192, 16, v178
	v_and_b32_e32 v193, 0xffff0000, v178
	v_lshlrev_b32_e32 v178, 16, v179
	v_and_b32_e32 v179, 0xffff0000, v179
	v_pk_add_f32 v[142:143], v[142:143], v[176:177]
	v_pk_add_f32 v[140:141], v[140:141], v[190:191]
	v_pk_add_f32 v[176:177], v[138:139], v[178:179]
	v_pk_add_f32 v[138:139], v[136:137], v[192:193]
	v_mul_f32_e32 v136, v141, v141
	v_mul_f32_e32 v137, v143, v143
	v_fmac_f32_e32 v136, v140, v140
	v_fmac_f32_e32 v137, v142, v142
	v_add_f32_e32 v136, v136, v137
	v_mul_f32_e32 v137, v139, v139
	v_fmac_f32_e32 v137, v138, v138
	v_add_f32_e32 v136, v137, v136
	v_mul_f32_e32 v137, v177, v177
	v_fmac_f32_e32 v137, v176, v176
	v_add_f32_e32 v178, v137, v136
	v_cvt_pk_bf16_f32 v136, v140, v141
	v_cvt_pk_bf16_f32 v137, v142, v143
	v_cvt_pk_bf16_f32 v138, v138, v139
	v_cvt_pk_bf16_f32 v139, v176, v177
	global_store_dwordx4 v[170:171], v[136:139], off
	v_lshlrev_b32_e32 v140, 16, v188
	v_and_b32_e32 v141, 0xffff0000, v188
	v_lshlrev_b32_e32 v136, 16, v186
	v_and_b32_e32 v137, 0xffff0000, v186
	v_lshlrev_b32_e32 v138, 16, v187
	v_and_b32_e32 v139, 0xffff0000, v187
	v_lshlrev_b32_e32 v142, 16, v189
	v_and_b32_e32 v143, 0xffff0000, v189
	v_pk_add_f32 v[134:135], v[134:135], v[138:139]
	v_pk_add_f32 v[132:133], v[132:133], v[136:137]
	v_pk_add_f32 v[136:137], v[130:131], v[142:143]
	v_pk_add_f32 v[130:131], v[128:129], v[140:141]
	v_mul_f32_e32 v128, v133, v133
	v_mul_f32_e32 v129, v135, v135
	v_fmac_f32_e32 v128, v132, v132
	v_fmac_f32_e32 v129, v134, v134
	v_add_f32_e32 v128, v128, v129
	v_mul_f32_e32 v129, v131, v131
	v_fmac_f32_e32 v129, v130, v130
	v_add_f32_e32 v128, v129, v128
	v_mul_f32_e32 v129, v137, v137
	v_fmac_f32_e32 v129, v136, v136
	v_add_f32_e32 v128, v129, v128
	v_add_f32_e32 v138, v178, v128
	v_cvt_pk_bf16_f32 v128, v132, v133
	v_cvt_pk_bf16_f32 v129, v134, v135
	v_cvt_pk_bf16_f32 v130, v130, v131
	v_cvt_pk_bf16_f32 v131, v136, v137
	global_store_dwordx4 v[170:171], v[128:131], off offset:256
	s_nop 1
	v_and_b32_e32 v129, 64, v212
	v_xor_b32_e32 v128, 16, v212
	v_add_u32_e32 v129, 64, v129
	v_cmp_lt_i32_e32 vcc, v128, v129
	v_xor_b32_e32 v130, 32, v212
	s_nop 0
	v_cndmask_b32_e32 v128, v212, v128, vcc
	v_lshlrev_b32_e32 v140, 2, v128
	v_mov_b32_e32 v128, v138
	s_nop 1
	v_permlane16_swap_b32_e32 v138, v128
	v_cmp_lt_i32_e32 vcc, v130, v129
	s_waitcnt lgkmcnt(0)
	v_add_f32_e32 v128, v138, v128
	v_cndmask_b32_e32 v129, v212, v130, vcc
	v_lshlrev_b32_e32 v141, 2, v129
	v_mov_b32_e32 v129, v128
	s_nop 1
	v_permlane32_swap_b32_e32 v128, v129
	s_and_saveexec_b64 s[22:23], s[4:5]
	s_cbranch_execz .LBB0_912
	v_lshlrev_b64 v[130:131], 6, v[164:165]
	v_lshl_add_u64 v[130:131], s[40:41], 0, v[130:131]
	v_lshl_add_u64 v[130:131], s[8:9], 2, v[130:131]
	s_lshl_b32 s68, s56, 2
	v_lshl_add_u64 v[130:131], v[130:131], 0, s[68:69]
	s_waitcnt lgkmcnt(0)
	v_add_f32_e32 v128, v128, v129
	global_store_dword v[130:131], v128, off
.LBB0_912:
	s_or_b64 exec, exec, s[22:23]
	v_or_b32_e32 v136, 32, v164
	v_ashrrev_i32_e32 v137, 31, v136
	s_waitcnt lgkmcnt(0)
; __device__ __forceinline__ unsigned cvt_pk_bf16(float lo, float hi) { unsigned r; asm volatile("v_cvt_pk_bf16_f32 %0, %1, %2" : "=v"(r) : "v"(lo), "v"(hi)); return r; }
; __device__ __forceinline__ float bflo(unsigned w) { return __uint_as_float(w << 16); }
; __device__ __forceinline__ float bfhi(unsigned w) { return __uint_as_float(w & 0xffff0000u); }
;     __device__ __forceinline__ void operator()(const f32x4 (&acc)[2][2][4][2], const Unit& u, int wr, int wc, int fr, int fq) const {
;     ...
; #pragma unroll
;         for (int g = 0; g < 8; ++g) { const int ai = g >> 2, m = g & 3; const int row = row0 + ai * HALF + m * 16; const size_t off = (size_t)row * 1024 + col0; float ss = 0.f;
;             if (g < 7) { const int g1 = g + 1; const size_t offn = (size_t)(row0 + (g1 >> 2) * HALF + (g1 & 3) * 16) * 1024 + col0;
; #pragma unroll
;                 for (int bj = 0; bj < 2; ++bj) nxt[bj] = *(const u32x4*)(xb + offn + bj * HALF); }
; #pragma unroll
;             for (int bj = 0; bj < 2; ++bj) { const u32x4 c = cur[bj];
;                 const f32x4 b0 = (f32x4){bflo(c[0]), bfhi(c[0]), bflo(c[1]), bfhi(c[1])}, b1 = (f32x4){bflo(c[2]), bfhi(c[2]), bflo(c[3]), bfhi(c[3])};
;                 const f32x4 v0 = b0 + (acc[ai][bj][m][0] + bv[bj][0]) * scale, v1 = b1 + (acc[ai][bj][m][1] + bv[bj][1]) * scale;
;                 ss += (v0[0] * v0[0] + v0[1] * v0[1]) + (v0[2] * v0[2] + v0[3] * v0[3]) + (v1[0] * v1[0] + v1[1] * v1[1]) + (v1[2] * v1[2] + v1[3] * v1[3]);
;                 u32x4 w; w.x = cvt_pk_bf16(v0[0], v0[1]); w.y = cvt_pk_bf16(v0[2], v0[3]); w.z = cvt_pk_bf16(v1[0], v1[1]); w.w = cvt_pk_bf16(v1[2], v1[3]);
;                 *(u32x4*)(xb + off + bj * HALF) = w; }
;             ss += __shfl_xor(ss, 16); ss += __shfl_xor(ss, 32);
;             if (fq == 0) partn[(size_t)row * 16 + u.pn * 4 + wc] = ss;
	v_lshlrev_b64 v[128:129], 11, v[136:137]
	v_lshl_add_u64 v[128:129], s[18:19], 0, v[128:129]
	v_lshl_add_u64 v[138:139], v[162:163], 1, v[128:129]
	global_load_dwordx4 v[132:135], v[138:139], off
	global_load_dwordx4 v[128:131], v[138:139], off offset:256
	v_lshlrev_b32_e32 v142, 16, v148
	v_and_b32_e32 v143, 0xffff0000, v148
	v_lshlrev_b32_e32 v148, 16, v149
	v_and_b32_e32 v149, 0xffff0000, v149
	v_pk_add_f32 v[126:127], v[126:127], v[102:103]
	v_pk_add_f32 v[124:125], v[124:125], v[100:101]
	v_lshlrev_b32_e32 v170, 16, v150
	v_and_b32_e32 v171, 0xffff0000, v150
	v_lshlrev_b32_e32 v150, 16, v151
	v_and_b32_e32 v151, 0xffff0000, v151
	v_pk_add_f32 v[126:127], v[126:127], v[148:149]
	v_pk_add_f32 v[124:125], v[124:125], v[142:143]
	v_pk_add_f32 v[122:123], v[122:123], v[94:95]
	v_pk_add_f32 v[120:121], v[120:121], v[92:93]
	v_pk_add_f32 v[142:143], v[122:123], v[150:151]
	v_pk_add_f32 v[122:123], v[120:121], v[170:171]
	v_mul_f32_e32 v120, v125, v125
	v_mul_f32_e32 v121, v127, v127
	v_fmac_f32_e32 v120, v124, v124
	v_fmac_f32_e32 v121, v126, v126
	v_add_f32_e32 v120, v120, v121
	v_mul_f32_e32 v121, v123, v123
	v_fmac_f32_e32 v121, v122, v122
	v_add_f32_e32 v120, v121, v120
	v_mul_f32_e32 v121, v143, v143
	v_fmac_f32_e32 v121, v142, v142
	v_add_f32_e32 v148, v121, v120
	v_cvt_pk_bf16_f32 v120, v124, v125
	v_cvt_pk_bf16_f32 v121, v126, v127
	v_lshlrev_b32_e32 v124, 16, v144
	v_and_b32_e32 v125, 0xffff0000, v144
	v_lshlrev_b32_e32 v126, 16, v145
	v_and_b32_e32 v127, 0xffff0000, v145
	v_pk_add_f32 v[118:119], v[118:119], v[90:91]
	v_pk_add_f32 v[116:117], v[116:117], v[88:89]
	v_lshlrev_b32_e32 v144, 16, v146
	v_and_b32_e32 v145, 0xffff0000, v146
	v_pk_add_f32 v[118:119], v[118:119], v[126:127]
	v_pk_add_f32 v[116:117], v[116:117], v[124:125]
	v_pk_add_f32 v[112:113], v[112:113], v[84:85]
	v_lshlrev_b32_e32 v146, 16, v147
	v_pk_add_f32 v[126:127], v[112:113], v[144:145]
	v_mul_f32_e32 v112, v117, v117
	v_mul_f32_e32 v113, v119, v119
	v_fmac_f32_e32 v112, v116, v116
	v_fmac_f32_e32 v113, v118, v118
	v_and_b32_e32 v147, 0xffff0000, v147
	v_pk_add_f32 v[114:115], v[114:115], v[86:87]
	v_add_f32_e32 v112, v112, v113
	v_mul_f32_e32 v113, v127, v127
	v_pk_add_f32 v[124:125], v[114:115], v[146:147]
	v_fmac_f32_e32 v113, v126, v126
	v_add_f32_e32 v112, v113, v112
	v_mul_f32_e32 v113, v125, v125
	v_fmac_f32_e32 v113, v124, v124
	v_add_f32_e32 v112, v113, v112
	v_add_f32_e32 v112, v148, v112
	v_mov_b32_e32 v113, v112
	s_nop 1
	v_permlane16_swap_b32_e32 v112, v113
	v_cvt_pk_bf16_f32 v122, v122, v123
	v_cvt_pk_bf16_f32 v123, v142, v143
	global_store_dwordx4 v[168:169], v[120:123], off
	v_cvt_pk_bf16_f32 v114, v116, v117
	s_waitcnt lgkmcnt(0)
	v_add_f32_e32 v112, v112, v113
	v_mov_b32_e32 v113, v112
	s_nop 1
	v_permlane32_swap_b32_e32 v112, v113
	v_cvt_pk_bf16_f32 v115, v118, v119
	v_cvt_pk_bf16_f32 v116, v126, v127
	v_cvt_pk_bf16_f32 v117, v124, v125
	global_store_dwordx4 v[168:169], v[114:117], off offset:256
	s_and_saveexec_b64 s[22:23], s[4:5]
	s_cbranch_execz .LBB0_914
	v_lshlrev_b64 v[114:115], 6, v[166:167]
	v_lshl_add_u64 v[114:115], s[40:41], 0, v[114:115]
	v_lshl_add_u64 v[114:115], s[8:9], 2, v[114:115]
	s_lshl_b32 s68, s56, 2
	v_lshl_add_u64 v[114:115], v[114:115], 0, s[68:69]
	s_waitcnt lgkmcnt(0)
	v_add_f32_e32 v112, v112, v113
	global_store_dword v[114:115], v112, off
.LBB0_914:
	s_or_b64 exec, exec, s[22:23]
	v_or_b32_e32 v120, 48, v164
	v_ashrrev_i32_e32 v121, 31, v120
	s_waitcnt lgkmcnt(0)
	v_lshlrev_b64 v[112:113], 11, v[120:121]
	v_lshl_add_u64 v[112:113], s[18:19], 0, v[112:113]
	v_lshl_add_u64 v[122:123], v[162:163], 1, v[112:113]
	global_load_dwordx4 v[116:119], v[122:123], off
	global_load_dwordx4 v[112:115], v[122:123], off offset:256
	s_waitcnt vmcnt(5)
	v_lshlrev_b32_e32 v124, 16, v132
	v_and_b32_e32 v125, 0xffff0000, v132
	v_lshlrev_b32_e32 v126, 16, v133
	v_and_b32_e32 v127, 0xffff0000, v133
	v_pk_add_f32 v[110:111], v[110:111], v[102:103]
	v_pk_add_f32 v[108:109], v[108:109], v[100:101]
	v_lshlrev_b32_e32 v132, 16, v134
	v_and_b32_e32 v133, 0xffff0000, v134
	v_lshlrev_b32_e32 v134, 16, v135
	v_and_b32_e32 v135, 0xffff0000, v135
	v_pk_add_f32 v[110:111], v[110:111], v[126:127]
	v_pk_add_f32 v[108:109], v[108:109], v[124:125]
	v_pk_add_f32 v[106:107], v[106:107], v[94:95]
	v_pk_add_f32 v[104:105], v[104:105], v[92:93]
	v_pk_add_f32 v[124:125], v[106:107], v[134:135]
	v_pk_add_f32 v[106:107], v[104:105], v[132:133]
	v_mul_f32_e32 v104, v109, v109
	v_mul_f32_e32 v105, v111, v111
	v_fmac_f32_e32 v104, v108, v108
	v_fmac_f32_e32 v105, v110, v110
	v_add_f32_e32 v104, v104, v105
	v_mul_f32_e32 v105, v107, v107
	v_fmac_f32_e32 v105, v106, v106
	v_add_f32_e32 v104, v105, v104
	v_mul_f32_e32 v105, v125, v125
	v_fmac_f32_e32 v105, v124, v124
	v_add_f32_e32 v132, v105, v104
	v_cvt_pk_bf16_f32 v104, v108, v109
	v_cvt_pk_bf16_f32 v105, v110, v111
	s_waitcnt vmcnt(4)
	v_lshlrev_b32_e32 v108, 16, v128
	v_and_b32_e32 v109, 0xffff0000, v128
	v_lshlrev_b32_e32 v110, 16, v129
	v_and_b32_e32 v111, 0xffff0000, v129
	v_pk_add_f32 v[98:99], v[98:99], v[90:91]
	v_pk_add_f32 v[96:97], v[96:97], v[88:89]
	v_lshlrev_b32_e32 v126, 16, v130
	v_and_b32_e32 v127, 0xffff0000, v130
	v_pk_add_f32 v[98:99], v[98:99], v[110:111]
	v_pk_add_f32 v[96:97], v[96:97], v[108:109]
	v_pk_add_f32 v[80:81], v[80:81], v[84:85]
	v_lshlrev_b32_e32 v128, 16, v131
	v_pk_add_f32 v[108:109], v[80:81], v[126:127]
	v_mul_f32_e32 v80, v97, v97
	v_mul_f32_e32 v81, v99, v99
	v_fmac_f32_e32 v80, v96, v96
	v_fmac_f32_e32 v81, v98, v98
	v_and_b32_e32 v129, 0xffff0000, v131
	v_pk_add_f32 v[82:83], v[82:83], v[86:87]
	v_add_f32_e32 v80, v80, v81
	v_mul_f32_e32 v81, v109, v109
	v_pk_add_f32 v[82:83], v[82:83], v[128:129]
	v_fmac_f32_e32 v81, v108, v108
	v_add_f32_e32 v80, v81, v80
	v_mul_f32_e32 v81, v83, v83
	v_fmac_f32_e32 v81, v82, v82
	v_add_f32_e32 v80, v81, v80
	v_add_f32_e32 v80, v132, v80
	v_mov_b32_e32 v81, v80
	s_nop 1
	v_permlane16_swap_b32_e32 v80, v81
	v_cvt_pk_bf16_f32 v106, v106, v107
	v_cvt_pk_bf16_f32 v107, v124, v125
	global_store_dwordx4 v[138:139], v[104:107], off
	v_cvt_pk_bf16_f32 v96, v96, v97
	s_waitcnt lgkmcnt(0)
	v_add_f32_e32 v80, v80, v81
	v_mov_b32_e32 v81, v80
	s_nop 1
	v_permlane32_swap_b32_e32 v80, v81
	v_cvt_pk_bf16_f32 v97, v98, v99
	v_cvt_pk_bf16_f32 v98, v108, v109
	v_cvt_pk_bf16_f32 v99, v82, v83
	global_store_dwordx4 v[138:139], v[96:99], off offset:256
	s_and_saveexec_b64 s[22:23], s[4:5]
	s_cbranch_execz .LBB0_916
	v_lshlrev_b64 v[82:83], 6, v[136:137]
	v_lshl_add_u64 v[82:83], s[40:41], 0, v[82:83]
	v_lshl_add_u64 v[82:83], s[8:9], 2, v[82:83]
	s_lshl_b32 s68, s56, 2
	v_lshl_add_u64 v[82:83], v[82:83], 0, s[68:69]
	s_waitcnt lgkmcnt(0)
	v_add_f32_e32 v80, v80, v81
	global_store_dword v[82:83], v80, off
; __device__ __forceinline__ unsigned cvt_pk_bf16(float lo, float hi) { unsigned r; asm volatile("v_cvt_pk_bf16_f32 %0, %1, %2" : "=v"(r) : "v"(lo), "v"(hi)); return r; }
; __device__ __forceinline__ float bflo(unsigned w) { return __uint_as_float(w << 16); }
; __device__ __forceinline__ float bfhi(unsigned w) { return __uint_as_float(w & 0xffff0000u); }
;     __device__ __forceinline__ void operator()(const f32x4 (&acc)[2][2][4][2], const Unit& u, int wr, int wc, int fr, int fq) const {
;     ...
; #pragma unroll
;         for (int g = 0; g < 8; ++g) { const int ai = g >> 2, m = g & 3; const int row = row0 + ai * HALF + m * 16; const size_t off = (size_t)row * 1024 + col0; float ss = 0.f;
;             if (g < 7) { const int g1 = g + 1; const size_t offn = (size_t)(row0 + (g1 >> 2) * HALF + (g1 & 3) * 16) * 1024 + col0;
; #pragma unroll
;                 for (int bj = 0; bj < 2; ++bj) nxt[bj] = *(const u32x4*)(xb + offn + bj * HALF); }
; #pragma unroll
;             for (int bj = 0; bj < 2; ++bj) { const u32x4 c = cur[bj];
;                 const f32x4 b0 = (f32x4){bflo(c[0]), bfhi(c[0]), bflo(c[1]), bfhi(c[1])}, b1 = (f32x4){bflo(c[2]), bfhi(c[2]), bflo(c[3]), bfhi(c[3])};
;                 const f32x4 v0 = b0 + (acc[ai][bj][m][0] + bv[bj][0]) * scale, v1 = b1 + (acc[ai][bj][m][1] + bv[bj][1]) * scale;
;                 ss += (v0[0] * v0[0] + v0[1] * v0[1]) + (v0[2] * v0[2] + v0[3] * v0[3]) + (v1[0] * v1[0] + v1[1] * v1[1]) + (v1[2] * v1[2] + v1[3] * v1[3]);
;                 u32x4 w; w.x = cvt_pk_bf16(v0[0], v0[1]); w.y = cvt_pk_bf16(v0[2], v0[3]); w.z = cvt_pk_bf16(v1[0], v1[1]); w.w = cvt_pk_bf16(v1[2], v1[3]);
;                 *(u32x4*)(xb + off + bj * HALF) = w; }
;             ss += __shfl_xor(ss, 16); ss += __shfl_xor(ss, 32);
;             if (fq == 0) partn[(size_t)row * 16 + u.pn * 4 + wc] = ss;
.LBB0_916:
	s_or_b64 exec, exec, s[22:23]
	v_add_u32_e32 v104, 0x80, v164
	v_ashrrev_i32_e32 v105, 31, v104
	s_waitcnt lgkmcnt(0)
	v_lshlrev_b64 v[80:81], 11, v[104:105]
	v_lshl_add_u64 v[80:81], s[18:19], 0, v[80:81]
	v_lshl_add_u64 v[106:107], v[162:163], 1, v[80:81]
	global_load_dwordx4 v[96:99], v[106:107], off
	global_load_dwordx4 v[80:83], v[106:107], off offset:256
	s_waitcnt vmcnt(5)
	v_lshlrev_b32_e32 v108, 16, v116
	v_and_b32_e32 v109, 0xffff0000, v116
	v_lshlrev_b32_e32 v110, 16, v117
	v_and_b32_e32 v111, 0xffff0000, v117
	v_pk_add_f32 v[78:79], v[78:79], v[102:103]
	v_pk_add_f32 v[76:77], v[76:77], v[100:101]
	v_lshlrev_b32_e32 v116, 16, v118
	v_and_b32_e32 v117, 0xffff0000, v118
	v_lshlrev_b32_e32 v118, 16, v119
	v_and_b32_e32 v119, 0xffff0000, v119
	v_pk_add_f32 v[78:79], v[78:79], v[110:111]
	v_pk_add_f32 v[76:77], v[76:77], v[108:109]
	v_pk_add_f32 v[74:75], v[74:75], v[94:95]
	v_pk_add_f32 v[72:73], v[72:73], v[92:93]
	v_pk_add_f32 v[108:109], v[74:75], v[118:119]
	v_pk_add_f32 v[74:75], v[72:73], v[116:117]
	v_mul_f32_e32 v72, v77, v77
	v_mul_f32_e32 v73, v79, v79
	v_fmac_f32_e32 v72, v76, v76
	v_fmac_f32_e32 v73, v78, v78
	v_add_f32_e32 v72, v72, v73
	v_mul_f32_e32 v73, v75, v75
	v_fmac_f32_e32 v73, v74, v74
	v_add_f32_e32 v72, v73, v72
	v_mul_f32_e32 v73, v109, v109
	v_fmac_f32_e32 v73, v108, v108
	v_add_f32_e32 v116, v73, v72
	v_cvt_pk_bf16_f32 v72, v76, v77
	v_cvt_pk_bf16_f32 v73, v78, v79
	s_waitcnt vmcnt(4)
	v_lshlrev_b32_e32 v76, 16, v112
	v_and_b32_e32 v77, 0xffff0000, v112
	v_lshlrev_b32_e32 v78, 16, v113
	v_and_b32_e32 v79, 0xffff0000, v113
	v_pk_add_f32 v[70:71], v[70:71], v[90:91]
	v_pk_add_f32 v[68:69], v[68:69], v[88:89]
	v_lshlrev_b32_e32 v110, 16, v114
	v_and_b32_e32 v111, 0xffff0000, v114
	v_pk_add_f32 v[70:71], v[70:71], v[78:79]
	v_pk_add_f32 v[68:69], v[68:69], v[76:77]
	v_pk_add_f32 v[64:65], v[64:65], v[84:85]
	v_lshlrev_b32_e32 v112, 16, v115
	v_pk_add_f32 v[78:79], v[64:65], v[110:111]
	v_mul_f32_e32 v64, v69, v69
	v_mul_f32_e32 v65, v71, v71
	v_fmac_f32_e32 v64, v68, v68
	v_fmac_f32_e32 v65, v70, v70
	v_and_b32_e32 v113, 0xffff0000, v115
	v_pk_add_f32 v[66:67], v[66:67], v[86:87]
	v_add_f32_e32 v64, v64, v65
	v_mul_f32_e32 v65, v79, v79
	v_pk_add_f32 v[76:77], v[66:67], v[112:113]
	v_fmac_f32_e32 v65, v78, v78
	v_add_f32_e32 v64, v65, v64
	v_mul_f32_e32 v65, v77, v77
	v_fmac_f32_e32 v65, v76, v76
	v_add_f32_e32 v64, v65, v64
	v_add_f32_e32 v64, v116, v64
	v_mov_b32_e32 v65, v64
	s_nop 1
	v_permlane16_swap_b32_e32 v64, v65
	v_cvt_pk_bf16_f32 v74, v74, v75
	v_cvt_pk_bf16_f32 v75, v108, v109
	global_store_dwordx4 v[122:123], v[72:75], off
	v_cvt_pk_bf16_f32 v66, v68, v69
	s_waitcnt lgkmcnt(0)
	v_add_f32_e32 v64, v64, v65
	v_mov_b32_e32 v65, v64
	s_nop 1
	v_permlane32_swap_b32_e32 v64, v65
	v_cvt_pk_bf16_f32 v67, v70, v71
	v_cvt_pk_bf16_f32 v68, v78, v79
	v_cvt_pk_bf16_f32 v69, v76, v77
	global_store_dwordx4 v[122:123], v[66:69], off offset:256
	s_and_saveexec_b64 s[22:23], s[4:5]
	s_cbranch_execz .LBB0_918
	v_lshlrev_b64 v[66:67], 6, v[120:121]
	v_lshl_add_u64 v[66:67], s[40:41], 0, v[66:67]
	v_lshl_add_u64 v[66:67], s[8:9], 2, v[66:67]
	s_lshl_b32 s68, s56, 2
	v_lshl_add_u64 v[66:67], v[66:67], 0, s[68:69]
	s_waitcnt lgkmcnt(0)
	v_add_f32_e32 v64, v64, v65
	global_store_dword v[66:67], v64, off
.LBB0_918:
	s_or_b64 exec, exec, s[22:23]
	v_or_b32_e32 v72, 16, v104
	v_ashrrev_i32_e32 v73, 31, v72
	s_waitcnt lgkmcnt(0)
	v_lshlrev_b64 v[64:65], 11, v[72:73]
	v_lshl_add_u64 v[64:65], s[18:19], 0, v[64:65]
	v_lshl_add_u64 v[74:75], v[162:163], 1, v[64:65]
	global_load_dwordx4 v[68:71], v[74:75], off
	global_load_dwordx4 v[64:67], v[74:75], off offset:256
	s_waitcnt vmcnt(5)
	v_lshlrev_b32_e32 v76, 16, v96
	v_and_b32_e32 v77, 0xffff0000, v96
	v_lshlrev_b32_e32 v78, 16, v97
	v_and_b32_e32 v79, 0xffff0000, v97
	v_pk_add_f32 v[62:63], v[62:63], v[102:103]
	v_pk_add_f32 v[60:61], v[60:61], v[100:101]
	v_lshlrev_b32_e32 v96, 16, v98
	v_and_b32_e32 v97, 0xffff0000, v98
	v_lshlrev_b32_e32 v98, 16, v99
	v_and_b32_e32 v99, 0xffff0000, v99
	v_pk_add_f32 v[62:63], v[62:63], v[78:79]
	v_pk_add_f32 v[60:61], v[60:61], v[76:77]
	v_pk_add_f32 v[58:59], v[58:59], v[94:95]
	v_pk_add_f32 v[56:57], v[56:57], v[92:93]
	v_pk_add_f32 v[76:77], v[58:59], v[98:99]
	v_pk_add_f32 v[58:59], v[56:57], v[96:97]
	v_mul_f32_e32 v56, v61, v61
	v_mul_f32_e32 v57, v63, v63
	v_fmac_f32_e32 v56, v60, v60
	v_fmac_f32_e32 v57, v62, v62
	v_add_f32_e32 v56, v56, v57
	v_mul_f32_e32 v57, v59, v59
	v_fmac_f32_e32 v57, v58, v58
	v_add_f32_e32 v56, v57, v56
	v_mul_f32_e32 v57, v77, v77
	v_fmac_f32_e32 v57, v76, v76
	v_add_f32_e32 v96, v57, v56
	v_cvt_pk_bf16_f32 v56, v60, v61
	v_cvt_pk_bf16_f32 v57, v62, v63
	s_waitcnt vmcnt(4)
	v_lshlrev_b32_e32 v60, 16, v80
	v_and_b32_e32 v61, 0xffff0000, v80
	v_lshlrev_b32_e32 v62, 16, v81
	v_and_b32_e32 v63, 0xffff0000, v81
	v_pk_add_f32 v[54:55], v[54:55], v[90:91]
	v_pk_add_f32 v[52:53], v[52:53], v[88:89]
	v_lshlrev_b32_e32 v78, 16, v82
	v_and_b32_e32 v79, 0xffff0000, v82
	v_pk_add_f32 v[54:55], v[54:55], v[62:63]
	v_pk_add_f32 v[52:53], v[52:53], v[60:61]
	v_pk_add_f32 v[48:49], v[48:49], v[84:85]
	v_lshlrev_b32_e32 v80, 16, v83
	v_pk_add_f32 v[62:63], v[48:49], v[78:79]
	v_mul_f32_e32 v48, v53, v53
	v_mul_f32_e32 v49, v55, v55
	v_fmac_f32_e32 v48, v52, v52
	v_fmac_f32_e32 v49, v54, v54
	v_and_b32_e32 v81, 0xffff0000, v83
	v_pk_add_f32 v[50:51], v[50:51], v[86:87]
	v_add_f32_e32 v48, v48, v49
	v_mul_f32_e32 v49, v63, v63
	v_pk_add_f32 v[60:61], v[50:51], v[80:81]
	v_fmac_f32_e32 v49, v62, v62
	v_add_f32_e32 v48, v49, v48
	v_mul_f32_e32 v49, v61, v61
	v_fmac_f32_e32 v49, v60, v60
	v_add_f32_e32 v48, v49, v48
	v_add_f32_e32 v48, v96, v48
	v_mov_b32_e32 v49, v48
	s_nop 1
	v_permlane16_swap_b32_e32 v48, v49
	v_cvt_pk_bf16_f32 v58, v58, v59
	v_cvt_pk_bf16_f32 v59, v76, v77
	global_store_dwordx4 v[106:107], v[56:59], off
	v_cvt_pk_bf16_f32 v50, v52, v53
	s_waitcnt lgkmcnt(0)
	v_add_f32_e32 v48, v48, v49
	v_mov_b32_e32 v49, v48
	s_nop 1
	v_permlane32_swap_b32_e32 v48, v49
	v_cvt_pk_bf16_f32 v51, v54, v55
	v_cvt_pk_bf16_f32 v52, v62, v63
	v_cvt_pk_bf16_f32 v53, v60, v61
	global_store_dwordx4 v[106:107], v[50:53], off offset:256
	s_and_saveexec_b64 s[22:23], s[4:5]
	s_cbranch_execz .LBB0_920
	v_lshlrev_b64 v[50:51], 6, v[104:105]
	v_lshl_add_u64 v[50:51], s[40:41], 0, v[50:51]
	v_lshl_add_u64 v[50:51], s[8:9], 2, v[50:51]
	s_lshl_b32 s68, s56, 2
	v_lshl_add_u64 v[50:51], v[50:51], 0, s[68:69]
	s_waitcnt lgkmcnt(0)
	v_add_f32_e32 v48, v48, v49
	global_store_dword v[50:51], v48, off
; __device__ __forceinline__ unsigned cvt_pk_bf16(float lo, float hi) { unsigned r; asm volatile("v_cvt_pk_bf16_f32 %0, %1, %2" : "=v"(r) : "v"(lo), "v"(hi)); return r; }
; __device__ __forceinline__ float bflo(unsigned w) { return __uint_as_float(w << 16); }
; __device__ __forceinline__ float bfhi(unsigned w) { return __uint_as_float(w & 0xffff0000u); }
;     __device__ __forceinline__ void operator()(const f32x4 (&acc)[2][2][4][2], const Unit& u, int wr, int wc, int fr, int fq) const {
;     ...
; #pragma unroll
;         for (int g = 0; g < 8; ++g) { const int ai = g >> 2, m = g & 3; const int row = row0 + ai * HALF + m * 16; const size_t off = (size_t)row * 1024 + col0; float ss = 0.f;
;             if (g < 7) { const int g1 = g + 1; const size_t offn = (size_t)(row0 + (g1 >> 2) * HALF + (g1 & 3) * 16) * 1024 + col0;
; #pragma unroll
;                 for (int bj = 0; bj < 2; ++bj) nxt[bj] = *(const u32x4*)(xb + offn + bj * HALF); }
; #pragma unroll
;             for (int bj = 0; bj < 2; ++bj) { const u32x4 c = cur[bj];
;                 const f32x4 b0 = (f32x4){bflo(c[0]), bfhi(c[0]), bflo(c[1]), bfhi(c[1])}, b1 = (f32x4){bflo(c[2]), bfhi(c[2]), bflo(c[3]), bfhi(c[3])};
;                 const f32x4 v0 = b0 + (acc[ai][bj][m][0] + bv[bj][0]) * scale, v1 = b1 + (acc[ai][bj][m][1] + bv[bj][1]) * scale;
;                 ss += (v0[0] * v0[0] + v0[1] * v0[1]) + (v0[2] * v0[2] + v0[3] * v0[3]) + (v1[0] * v1[0] + v1[1] * v1[1]) + (v1[2] * v1[2] + v1[3] * v1[3]);
;                 u32x4 w; w.x = cvt_pk_bf16(v0[0], v0[1]); w.y = cvt_pk_bf16(v0[2], v0[3]); w.z = cvt_pk_bf16(v1[0], v1[1]); w.w = cvt_pk_bf16(v1[2], v1[3]);
;                 *(u32x4*)(xb + off + bj * HALF) = w; }
;             ss += __shfl_xor(ss, 16); ss += __shfl_xor(ss, 32);
;             if (fq == 0) partn[(size_t)row * 16 + u.pn * 4 + wc] = ss;
.LBB0_920:
	s_or_b64 exec, exec, s[22:23]
	v_or_b32_e32 v56, 32, v104
	v_ashrrev_i32_e32 v57, 31, v56
	s_waitcnt lgkmcnt(0)
	v_lshlrev_b64 v[48:49], 11, v[56:57]
	v_lshl_add_u64 v[48:49], s[18:19], 0, v[48:49]
	v_lshl_add_u64 v[58:59], v[162:163], 1, v[48:49]
	global_load_dwordx4 v[52:55], v[58:59], off
	global_load_dwordx4 v[48:51], v[58:59], off offset:256
	s_waitcnt vmcnt(5)
	v_lshlrev_b32_e32 v60, 16, v68
	v_and_b32_e32 v61, 0xffff0000, v68
	v_lshlrev_b32_e32 v62, 16, v69
	v_and_b32_e32 v63, 0xffff0000, v69
	v_pk_add_f32 v[46:47], v[46:47], v[102:103]
	v_pk_add_f32 v[44:45], v[44:45], v[100:101]
	v_lshlrev_b32_e32 v68, 16, v70
	v_and_b32_e32 v69, 0xffff0000, v70
	v_lshlrev_b32_e32 v70, 16, v71
	v_and_b32_e32 v71, 0xffff0000, v71
	v_pk_add_f32 v[46:47], v[46:47], v[62:63]
	v_pk_add_f32 v[44:45], v[44:45], v[60:61]
	v_pk_add_f32 v[42:43], v[42:43], v[94:95]
	v_pk_add_f32 v[40:41], v[40:41], v[92:93]
	v_pk_add_f32 v[60:61], v[42:43], v[70:71]
	v_pk_add_f32 v[42:43], v[40:41], v[68:69]
	v_mul_f32_e32 v40, v45, v45
	v_mul_f32_e32 v41, v47, v47
	v_fmac_f32_e32 v40, v44, v44
	v_fmac_f32_e32 v41, v46, v46
	v_add_f32_e32 v40, v40, v41
	v_mul_f32_e32 v41, v43, v43
	v_fmac_f32_e32 v41, v42, v42
	v_add_f32_e32 v40, v41, v40
	v_mul_f32_e32 v41, v61, v61
	v_fmac_f32_e32 v41, v60, v60
	v_add_f32_e32 v68, v41, v40
	v_cvt_pk_bf16_f32 v40, v44, v45
	v_cvt_pk_bf16_f32 v41, v46, v47
	s_waitcnt vmcnt(4)
	v_lshlrev_b32_e32 v44, 16, v64
	v_and_b32_e32 v45, 0xffff0000, v64
	v_lshlrev_b32_e32 v46, 16, v65
	v_and_b32_e32 v47, 0xffff0000, v65
	v_pk_add_f32 v[38:39], v[38:39], v[90:91]
	v_pk_add_f32 v[36:37], v[36:37], v[88:89]
	v_lshlrev_b32_e32 v62, 16, v66
	v_and_b32_e32 v63, 0xffff0000, v66
	v_pk_add_f32 v[38:39], v[38:39], v[46:47]
	v_pk_add_f32 v[36:37], v[36:37], v[44:45]
	v_pk_add_f32 v[32:33], v[32:33], v[84:85]
	v_lshlrev_b32_e32 v64, 16, v67
	v_pk_add_f32 v[46:47], v[32:33], v[62:63]
	v_mul_f32_e32 v32, v37, v37
	v_mul_f32_e32 v33, v39, v39
	v_fmac_f32_e32 v32, v36, v36
	v_fmac_f32_e32 v33, v38, v38
	v_and_b32_e32 v65, 0xffff0000, v67
	v_pk_add_f32 v[34:35], v[34:35], v[86:87]
	v_add_f32_e32 v32, v32, v33
	v_mul_f32_e32 v33, v47, v47
	v_pk_add_f32 v[44:45], v[34:35], v[64:65]
	v_fmac_f32_e32 v33, v46, v46
	v_add_f32_e32 v32, v33, v32
	v_mul_f32_e32 v33, v45, v45
	v_fmac_f32_e32 v33, v44, v44
	v_add_f32_e32 v32, v33, v32
	v_add_f32_e32 v32, v68, v32
	v_mov_b32_e32 v33, v32
	s_nop 1
	v_permlane16_swap_b32_e32 v32, v33
	v_cvt_pk_bf16_f32 v42, v42, v43
	v_cvt_pk_bf16_f32 v43, v60, v61
	global_store_dwordx4 v[74:75], v[40:43], off
	v_cvt_pk_bf16_f32 v34, v36, v37
	s_waitcnt lgkmcnt(0)
	v_add_f32_e32 v32, v32, v33
	v_mov_b32_e32 v33, v32
	s_nop 1
	v_permlane32_swap_b32_e32 v32, v33
	v_cvt_pk_bf16_f32 v35, v38, v39
	v_cvt_pk_bf16_f32 v36, v46, v47
	v_cvt_pk_bf16_f32 v37, v44, v45
	global_store_dwordx4 v[74:75], v[34:37], off offset:256
	s_and_saveexec_b64 s[22:23], s[4:5]
	s_cbranch_execz .LBB0_922
	v_lshlrev_b64 v[34:35], 6, v[72:73]
	v_lshl_add_u64 v[34:35], s[40:41], 0, v[34:35]
	v_lshl_add_u64 v[34:35], s[8:9], 2, v[34:35]
	s_lshl_b32 s68, s56, 2
	v_lshl_add_u64 v[34:35], v[34:35], 0, s[68:69]
	s_waitcnt lgkmcnt(0)
	v_add_f32_e32 v32, v32, v33
	global_store_dword v[34:35], v32, off
; __device__ __forceinline__ unsigned cvt_pk_bf16(float lo, float hi) { unsigned r; asm volatile("v_cvt_pk_bf16_f32 %0, %1, %2" : "=v"(r) : "v"(lo), "v"(hi)); return r; }
; __device__ __forceinline__ float bflo(unsigned w) { return __uint_as_float(w << 16); }
; __device__ __forceinline__ float bfhi(unsigned w) { return __uint_as_float(w & 0xffff0000u); }
;     __device__ __forceinline__ void operator()(const f32x4 (&acc)[2][2][4][2], const Unit& u, int wr, int wc, int fr, int fq) const {
;     ...
; #pragma unroll
;         for (int g = 0; g < 8; ++g) { const int ai = g >> 2, m = g & 3; const int row = row0 + ai * HALF + m * 16; const size_t off = (size_t)row * 1024 + col0; float ss = 0.f;
;             if (g < 7) { const int g1 = g + 1; const size_t offn = (size_t)(row0 + (g1 >> 2) * HALF + (g1 & 3) * 16) * 1024 + col0;
; #pragma unroll
;                 for (int bj = 0; bj < 2; ++bj) nxt[bj] = *(const u32x4*)(xb + offn + bj * HALF); }
; #pragma unroll
;             for (int bj = 0; bj < 2; ++bj) { const u32x4 c = cur[bj];
;                 const f32x4 b0 = (f32x4){bflo(c[0]), bfhi(c[0]), bflo(c[1]), bfhi(c[1])}, b1 = (f32x4){bflo(c[2]), bfhi(c[2]), bflo(c[3]), bfhi(c[3])};
;                 const f32x4 v0 = b0 + (acc[ai][bj][m][0] + bv[bj][0]) * scale, v1 = b1 + (acc[ai][bj][m][1] + bv[bj][1]) * scale;
;                 ss += (v0[0] * v0[0] + v0[1] * v0[1]) + (v0[2] * v0[2] + v0[3] * v0[3]) + (v1[0] * v1[0] + v1[1] * v1[1]) + (v1[2] * v1[2] + v1[3] * v1[3]);
;                 u32x4 w; w.x = cvt_pk_bf16(v0[0], v0[1]); w.y = cvt_pk_bf16(v0[2], v0[3]); w.z = cvt_pk_bf16(v1[0], v1[1]); w.w = cvt_pk_bf16(v1[2], v1[3]);
;                 *(u32x4*)(xb + off + bj * HALF) = w; }
;             ss += __shfl_xor(ss, 16); ss += __shfl_xor(ss, 32);
;             if (fq == 0) partn[(size_t)row * 16 + u.pn * 4 + wc] = ss;
.LBB0_922:
	s_or_b64 exec, exec, s[22:23]
	v_or_b32_e32 v40, 48, v104
	v_ashrrev_i32_e32 v41, 31, v40
	s_waitcnt lgkmcnt(0)
	v_lshlrev_b64 v[32:33], 11, v[40:41]
	v_lshl_add_u64 v[32:33], s[18:19], 0, v[32:33]
	v_lshl_add_u64 v[42:43], v[162:163], 1, v[32:33]
	global_load_dwordx4 v[36:39], v[42:43], off
	global_load_dwordx4 v[32:35], v[42:43], off offset:256
	s_waitcnt vmcnt(5)
	v_lshlrev_b32_e32 v44, 16, v52
	v_and_b32_e32 v45, 0xffff0000, v52
	v_lshlrev_b32_e32 v46, 16, v53
	v_and_b32_e32 v47, 0xffff0000, v53
	v_pk_add_f32 v[30:31], v[30:31], v[102:103]
	v_pk_add_f32 v[28:29], v[28:29], v[100:101]
	v_lshlrev_b32_e32 v52, 16, v54
	v_and_b32_e32 v53, 0xffff0000, v54
	v_lshlrev_b32_e32 v54, 16, v55
	v_and_b32_e32 v55, 0xffff0000, v55
	v_pk_add_f32 v[30:31], v[30:31], v[46:47]
	v_pk_add_f32 v[28:29], v[28:29], v[44:45]
	v_pk_add_f32 v[26:27], v[26:27], v[94:95]
	v_pk_add_f32 v[24:25], v[24:25], v[92:93]
	v_pk_add_f32 v[44:45], v[26:27], v[54:55]
	v_pk_add_f32 v[26:27], v[24:25], v[52:53]
	v_mul_f32_e32 v24, v29, v29
	v_mul_f32_e32 v25, v31, v31
	v_fmac_f32_e32 v24, v28, v28
	v_fmac_f32_e32 v25, v30, v30
	v_add_f32_e32 v24, v24, v25
	v_mul_f32_e32 v25, v27, v27
	v_fmac_f32_e32 v25, v26, v26
	v_add_f32_e32 v24, v25, v24
	v_mul_f32_e32 v25, v45, v45
	v_fmac_f32_e32 v25, v44, v44
	v_add_f32_e32 v52, v25, v24
	v_cvt_pk_bf16_f32 v24, v28, v29
	v_cvt_pk_bf16_f32 v25, v30, v31
	s_waitcnt vmcnt(4)
	v_lshlrev_b32_e32 v28, 16, v48
	v_and_b32_e32 v29, 0xffff0000, v48
	v_lshlrev_b32_e32 v30, 16, v49
	v_and_b32_e32 v31, 0xffff0000, v49
	v_pk_add_f32 v[22:23], v[22:23], v[90:91]
	v_pk_add_f32 v[20:21], v[20:21], v[88:89]
	v_lshlrev_b32_e32 v46, 16, v50
	v_and_b32_e32 v47, 0xffff0000, v50
	v_pk_add_f32 v[22:23], v[22:23], v[30:31]
	v_pk_add_f32 v[20:21], v[20:21], v[28:29]
	v_pk_add_f32 v[16:17], v[16:17], v[84:85]
	v_lshlrev_b32_e32 v48, 16, v51
	v_pk_add_f32 v[30:31], v[16:17], v[46:47]
	v_mul_f32_e32 v16, v21, v21
	v_mul_f32_e32 v17, v23, v23
	v_fmac_f32_e32 v16, v20, v20
	v_fmac_f32_e32 v17, v22, v22
	v_and_b32_e32 v49, 0xffff0000, v51
	v_pk_add_f32 v[18:19], v[18:19], v[86:87]
	v_add_f32_e32 v16, v16, v17
	v_mul_f32_e32 v17, v31, v31
	v_pk_add_f32 v[28:29], v[18:19], v[48:49]
	v_fmac_f32_e32 v17, v30, v30
	v_add_f32_e32 v16, v17, v16
	v_mul_f32_e32 v17, v29, v29
	v_fmac_f32_e32 v17, v28, v28
	v_add_f32_e32 v16, v17, v16
	v_add_f32_e32 v16, v52, v16
	v_mov_b32_e32 v17, v16
	s_nop 1
	v_permlane16_swap_b32_e32 v16, v17
	v_cvt_pk_bf16_f32 v26, v26, v27
	v_cvt_pk_bf16_f32 v27, v44, v45
	global_store_dwordx4 v[58:59], v[24:27], off
	v_cvt_pk_bf16_f32 v18, v20, v21
	s_waitcnt lgkmcnt(0)
	v_add_f32_e32 v16, v16, v17
	v_mov_b32_e32 v17, v16
	s_nop 1
	v_permlane32_swap_b32_e32 v16, v17
	v_cvt_pk_bf16_f32 v19, v22, v23
	v_cvt_pk_bf16_f32 v20, v30, v31
	v_cvt_pk_bf16_f32 v21, v28, v29
	global_store_dwordx4 v[58:59], v[18:21], off offset:256
	s_and_saveexec_b64 s[22:23], s[4:5]
	s_cbranch_execz .LBB0_924
	v_lshlrev_b64 v[18:19], 6, v[56:57]
	v_lshl_add_u64 v[18:19], s[40:41], 0, v[18:19]
	v_lshl_add_u64 v[18:19], s[8:9], 2, v[18:19]
	s_lshl_b32 s68, s56, 2
	v_lshl_add_u64 v[18:19], v[18:19], 0, s[68:69]
	s_waitcnt lgkmcnt(0)
	v_add_f32_e32 v16, v16, v17
	global_store_dword v[18:19], v16, off
.LBB0_924:
	s_or_b64 exec, exec, s[22:23]
	s_waitcnt vmcnt(3)
	v_lshlrev_b32_e32 v16, 16, v36
	s_waitcnt lgkmcnt(0)
	v_and_b32_e32 v17, 0xffff0000, v36
	v_lshlrev_b32_e32 v18, 16, v37
	v_and_b32_e32 v19, 0xffff0000, v37
	v_pk_add_f32 v[14:15], v[14:15], v[102:103]
	v_pk_add_f32 v[12:13], v[12:13], v[100:101]
	v_lshlrev_b32_e32 v20, 16, v38
	v_and_b32_e32 v21, 0xffff0000, v38
	v_lshlrev_b32_e32 v22, 16, v39
	v_and_b32_e32 v23, 0xffff0000, v39
	v_pk_add_f32 v[14:15], v[14:15], v[18:19]
	v_pk_add_f32 v[12:13], v[12:13], v[16:17]
	v_pk_add_f32 v[10:11], v[10:11], v[94:95]
	v_pk_add_f32 v[8:9], v[8:9], v[92:93]
	v_pk_add_f32 v[16:17], v[10:11], v[22:23]
	v_pk_add_f32 v[10:11], v[8:9], v[20:21]
	v_mul_f32_e32 v8, v13, v13
	v_mul_f32_e32 v9, v15, v15
	v_fmac_f32_e32 v8, v12, v12
	v_fmac_f32_e32 v9, v14, v14
	v_add_f32_e32 v8, v8, v9
	v_mul_f32_e32 v9, v11, v11
	v_fmac_f32_e32 v9, v10, v10
	v_add_f32_e32 v8, v9, v8
	v_mul_f32_e32 v9, v17, v17
	v_fmac_f32_e32 v9, v16, v16
	v_add_f32_e32 v22, v9, v8
	v_cvt_pk_bf16_f32 v8, v12, v13
	v_cvt_pk_bf16_f32 v9, v14, v15
	s_waitcnt vmcnt(2)
	v_lshlrev_b32_e32 v12, 16, v32
	v_and_b32_e32 v13, 0xffff0000, v32
	v_lshlrev_b32_e32 v14, 16, v33
	v_and_b32_e32 v15, 0xffff0000, v33
	v_pk_add_f32 v[6:7], v[6:7], v[90:91]
	v_pk_add_f32 v[4:5], v[4:5], v[88:89]
	v_lshlrev_b32_e32 v18, 16, v34
	v_and_b32_e32 v19, 0xffff0000, v34
	v_pk_add_f32 v[6:7], v[6:7], v[14:15]
	v_pk_add_f32 v[4:5], v[4:5], v[12:13]
	v_pk_add_f32 v[0:1], v[0:1], v[84:85]
	v_lshlrev_b32_e32 v20, 16, v35
	v_pk_add_f32 v[14:15], v[0:1], v[18:19]
	v_mul_f32_e32 v0, v5, v5
	v_mul_f32_e32 v1, v7, v7
	v_fmac_f32_e32 v0, v4, v4
	v_fmac_f32_e32 v1, v6, v6
	v_and_b32_e32 v21, 0xffff0000, v35
	v_pk_add_f32 v[2:3], v[2:3], v[86:87]
	v_add_f32_e32 v0, v0, v1
	v_mul_f32_e32 v1, v15, v15
	v_pk_add_f32 v[12:13], v[2:3], v[20:21]
	v_fmac_f32_e32 v1, v14, v14
	v_add_f32_e32 v0, v1, v0
	v_mul_f32_e32 v1, v13, v13
	v_fmac_f32_e32 v1, v12, v12
	v_add_f32_e32 v0, v1, v0
	v_add_f32_e32 v0, v22, v0
	v_mov_b32_e32 v1, v0
	s_nop 1
	v_permlane16_swap_b32_e32 v0, v1
	v_cvt_pk_bf16_f32 v10, v10, v11
	v_cvt_pk_bf16_f32 v11, v16, v17
	global_store_dwordx4 v[42:43], v[8:11], off
	v_cvt_pk_bf16_f32 v2, v4, v5
	s_waitcnt lgkmcnt(0)
	v_add_f32_e32 v0, v0, v1
	v_mov_b32_e32 v1, v0
	s_nop 1
	v_permlane32_swap_b32_e32 v0, v1
	v_cvt_pk_bf16_f32 v3, v6, v7
	v_cvt_pk_bf16_f32 v4, v14, v15
	v_cvt_pk_bf16_f32 v5, v12, v13
	global_store_dwordx4 v[42:43], v[2:5], off offset:256
	s_and_saveexec_b64 s[22:23], s[4:5]
	s_cbranch_execz .LBB0_926
	v_lshlrev_b64 v[2:3], 6, v[40:41]
	v_lshl_add_u64 v[2:3], s[40:41], 0, v[2:3]
	v_lshl_add_u64 v[2:3], s[8:9], 2, v[2:3]
	s_lshl_b32 s68, s56, 2
	v_lshl_add_u64 v[2:3], v[2:3], 0, s[68:69]
	s_waitcnt lgkmcnt(0)
	v_add_f32_e32 v0, v0, v1
	global_store_dword v[2:3], v0, off
